# norm passes: gain vectors kept in VGPRs (loaded once before the row loop), vmcnt waits re-derived so stores and next-row prefetch stay in flight; plus HGRN prep load hoisting, chain DMA on idle waves,
# speedup vs baseline: 1.0295x; 1.0221x over previous
; __device__ __forceinline__ void rms_row_to_bf16(const f32x4 (&v)[8], const float* gain, bf16_t* orow, int lane) {
;     const f32x4* gr = (const f32x4*)gain + lane;
;     float s = 0.f;
; #pragma unroll
;     for (int j = 0; j < 8; ++j) s += (v[j].x * v[j].x + v[j].y * v[j].y) + (v[j].z * v[j].z + v[j].w * v[j].w);
;     const float rstd = rsqrtf(wave_sum(s) * (1.f / D) + EPS);
; __global__ void __launch_bounds__(NTHR, 2) hybrid_fwd(Args args) {
;     ...
;         f32x4 xv[8];
;         { const f32x4* xr = (const f32x4*)(args.in[I_XP] + (size_t)gw * D) + lane;
; #pragma unroll
;           for (int j = 0; j < 8; ++j) xv[j] = __builtin_nontemporal_load(&xr[64 * j]); }
;         for (int m = gw; m < M; m += NGW) {
;             const int mn = m + NGW < M ? m + NGW : m;
;             const float* xrow = (mn < MP) ? args.in[I_XP] + (size_t)mn * D : args.in[I_XS] + (size_t)(mn - MP) * D;
;             f32x4 xn[8];
; #pragma unroll
;             for (int j = 0; j < 8; ++j) xn[j] = __builtin_nontemporal_load(&((const f32x4*)xrow + lane)[64 * j]);
;             rms_row_to_bf16(xv, args.in[I_F1PRE], XN + (size_t)m * D, lane);
.LBB0_19:
	s_waitcnt vmcnt(0)
	s_cmp_lt_i32 s74, 0x8800
	s_cbranch_scc0 .LBB0_22
	s_waitcnt lgkmcnt(0)
	s_load_dwordx4 s[8:11], s[42:43], 0x0
	s_load_dwordx4 s[12:15], s[42:43], 0x28
	s_ashr_i32 s75, s74, 31
	s_lshl_b64 s[4:5], s[74:75], 13
	v_mov_b32_e32 v35, 0
	s_waitcnt lgkmcnt(0)
	s_add_u32 s4, s8, s4
	s_addc_u32 s5, s9, s5
	v_lshlrev_b32_e32 v34, 4, v128
	v_lshl_add_u64 v[2:3], s[4:5], 0, v[34:35]
	s_movk_i32 s22, 0x1000
	v_add_co_u32_e32 v36, vcc, s22, v2
	global_load_dwordx4 v[30:33], v34, s[4:5] nt
	global_load_dwordx4 v[26:29], v34, s[4:5] offset:1024 nt
	global_load_dwordx4 v[18:21], v34, s[4:5] offset:2048 nt
	global_load_dwordx4 v[10:13], v34, s[4:5] offset:3072 nt
	v_addc_co_u32_e32 v37, vcc, 0, v3, vcc
	global_load_dwordx4 v[22:25], v[36:37], off nt
	global_load_dwordx4 v[14:17], v[36:37], off offset:1024 nt
	global_load_dwordx4 v[6:9], v[36:37], off offset:2048 nt
	global_load_dwordx4 v[2:5], v[36:37], off offset:3072 nt
	s_load_dwordx2 s[4:5], s[42:43], 0x40
	v_mbcnt_lo_u32_b32 v1, -1, 0
	s_ashr_i32 s73, s72, 31
	v_lshlrev_b32_e32 v46, 3, v128
	v_mov_b32_e32 v47, v35
	s_waitcnt lgkmcnt(0)
	v_lshl_add_u64 v[36:37], s[4:5], 0, v[34:35]
	v_mbcnt_hi_u32_b32 v34, -1, v1
	v_and_b32_e32 v1, 64, v34
	v_add_u32_e32 v38, 64, v1
	v_xor_b32_e32 v1, 1, v34
	v_cmp_lt_i32_e32 vcc, v1, v38
	v_xor_b32_e32 v39, 2, v34
	s_mov_b64 s[4:5], 0x1000
	v_cndmask_b32_e32 v1, v34, v1, vcc
	v_cmp_lt_i32_e32 vcc, v39, v38
	v_lshlrev_b32_e32 v1, 2, v1
	s_mov_b64 s[20:21], 0
	v_cndmask_b32_e32 v39, v34, v39, vcc
	v_lshlrev_b32_e32 v65, 2, v39
	v_xor_b32_e32 v39, 4, v34
	v_cmp_lt_i32_e32 vcc, v39, v38
	v_mov_b32_e32 v73, 0x358637bd
	s_mov_b32 s23, 0x800000
	v_cndmask_b32_e32 v39, v34, v39, vcc
	v_lshlrev_b32_e32 v67, 2, v39
	v_xor_b32_e32 v39, 8, v34
	v_cmp_lt_i32_e32 vcc, v39, v38
	s_mov_b32 s24, 0xad00000
	s_mov_b32 s25, s74
	v_cndmask_b32_e32 v39, v34, v39, vcc
	v_lshlrev_b32_e32 v69, 2, v39
	v_xor_b32_e32 v39, 16, v34
	v_cmp_lt_i32_e32 vcc, v39, v38
	s_nop 1
	v_cndmask_b32_e32 v39, v34, v39, vcc
	v_lshlrev_b32_e32 v71, 2, v39
	v_xor_b32_e32 v39, 32, v34
	v_cmp_lt_i32_e32 vcc, v39, v38
	s_nop 1
	v_cndmask_b32_e32 v34, v34, v39, vcc
	v_lshl_add_u64 v[38:39], v[36:37], 0, s[4:5]
	s_mov_b64 s[4:5], 0x1400
	v_lshl_add_u64 v[40:41], v[36:37], 0, s[4:5]
	s_mov_b64 s[4:5], 0x1800
	v_lshl_add_u64 v[42:43], v[36:37], 0, s[4:5]
	s_mov_b64 s[4:5], 0x1c00
	v_lshl_add_u64 v[44:45], v[36:37], 0, s[4:5]
	s_lshl_b64 s[4:5], s[74:75], 9
	s_add_u32 s4, s86, s4
	s_addc_u32 s5, s87, s5
	s_add_u32 s4, s4, 0x3ef00000
	s_addc_u32 s5, s5, 0
	s_lshl_b64 s[6:7], s[72:73], 9
	s_lshl_b64 s[16:17], s[74:75], 12
	s_add_u32 s16, s86, s16
	v_lshlrev_b32_e32 v72, 2, v34
	s_addc_u32 s17, s87, s17
	s_lshl_b64 s[18:19], s[72:73], 12
	v_lshlrev_b32_e32 v34, 4, v128
	global_load_dwordx4 v[132:135], v[36:37], off
	global_load_dwordx4 v[136:139], v[36:37], off offset:1024
	global_load_dwordx4 v[140:143], v[36:37], off offset:2048
	global_load_dwordx4 v[144:147], v[36:37], off offset:3072
	global_load_dwordx4 v[148:151], v[38:39], off
	global_load_dwordx4 v[152:155], v[40:41], off
	global_load_dwordx4 v[156:159], v[42:43], off
	global_load_dwordx4 v[160:163], v[44:45], off
.LBB0_21:
	s_nop 0
	s_waitcnt vmcnt(15)
	v_pk_mul_f32 v[52:53], v[30:31], v[30:31]
	s_waitcnt vmcnt(14)
	v_pk_mul_f32 v[48:49], v[26:27], v[26:27]
	v_pk_mul_f32 v[56:57], v[32:33], v[32:33]
	v_pk_mul_f32 v[50:51], v[28:29], v[28:29]
	s_waitcnt vmcnt(13)
	v_pk_mul_f32 v[60:61], v[20:21], v[20:21]
	v_pk_mul_f32 v[54:55], v[18:19], v[18:19]
	v_mov_b32_e32 v80, v52
	v_mov_b32_e32 v81, v48
	v_mov_b32_e32 v48, v53
	v_mov_b32_e32 v52, v56
	v_mov_b32_e32 v53, v50
	v_mov_b32_e32 v50, v57
	v_pk_mov_b32 v[56:57], v[54:55], v[60:61] op_sel:[1,0]
	v_mov_b32_e32 v55, v61
	v_pk_add_f32 v[48:49], v[80:81], v[48:49]
	v_pk_add_f32 v[50:51], v[52:53], v[50:51]
	s_waitcnt vmcnt(10)
	v_pk_mul_f32 v[62:63], v[16:17], v[16:17]
	v_pk_mul_f32 v[58:59], v[14:15], v[14:15]
	v_mul_f32_e32 v64, v10, v10
	v_mul_f32_e32 v66, v12, v12
	v_pk_add_f32 v[52:53], v[56:57], v[54:55]
	v_pk_add_f32 v[48:49], v[48:49], v[50:51]
	v_pk_mov_b32 v[60:61], v[58:59], v[62:63] op_sel:[1,0]
	v_mov_b32_e32 v59, v63
	v_pk_fma_f32 v[62:63], v[10:11], v[10:11], v[64:65] op_sel_hi:[1,1,0]
	v_pk_fma_f32 v[82:83], v[12:13], v[12:13], v[66:67] op_sel_hi:[1,1,0]
	v_pk_add_f32 v[52:53], v[52:53], v[52:53] op_sel_hi:[0,1]
	v_pk_add_f32 v[48:49], v[48:49], v[48:49] op_sel_hi:[0,1]
	v_mul_f32_e32 v62, v22, v22
	v_mul_f32_e32 v82, v23, v23
	v_mul_f32_e32 v52, v24, v24
	v_mul_f32_e32 v48, v25, v25
	v_pk_add_f32 v[50:51], v[62:63], v[82:83]
	v_pk_add_f32 v[48:49], v[52:53], v[48:49]
	s_waitcnt vmcnt(9)
	v_mul_f32_e32 v68, v6, v6
	v_mul_f32_e32 v70, v8, v8
	v_pk_add_f32 v[54:55], v[60:61], v[58:59]
	v_pk_add_f32 v[48:49], v[50:51], v[48:49]
	v_lshl_add_u64 v[78:79], s[16:17], 0, v[46:47]
	v_pk_fma_f32 v[84:85], v[6:7], v[6:7], v[68:69] op_sel_hi:[1,1,0]
	v_pk_fma_f32 v[86:87], v[8:9], v[8:9], v[70:71] op_sel_hi:[1,1,0]
	v_pk_add_f32 v[80:81], v[54:55], v[54:55] op_sel_hi:[0,1]
	v_pk_add_f32 v[82:83], v[48:49], v[48:49] op_sel_hi:[0,1]
	v_add_co_u32_e32 v94, vcc, s24, v78
	s_waitcnt vmcnt(8)
	v_mul_f32_e32 v84, v2, v2
	v_mul_f32_e32 v86, v3, v3
	v_mul_f32_e32 v80, v4, v4
	v_mul_f32_e32 v82, v5, v5
	v_addc_co_u32_e32 v95, vcc, 0, v79, vcc
	v_pk_add_f32 v[78:79], v[84:85], v[86:87]
	v_pk_add_f32 v[80:81], v[80:81], v[82:83]
	s_add_i32 s28, s25, s72
	v_pk_add_f32 v[96:97], v[78:79], v[80:81]
	s_cmp_lt_i32 s28, 0x8800
	v_add_f32_e32 v64, v96, v97
	ds_bpermute_b32 v66, v1, v64
	s_cselect_b32 s29, s28, s25
	s_add_i32 s30, s29, 0xffff8000
	s_ashr_i32 s31, s29, 31
	s_cmp_lt_i32 s29, 0x8000
	s_waitcnt lgkmcnt(0)
; __device__ __forceinline__ unsigned cvt_pk_bf16(float lo, float hi) { const f32x2_cv v = {lo, hi}; return __builtin_bit_cast(unsigned, __builtin_convertvector(v, bf16x2_cv)); }
; __device__ __forceinline__ void rms_row_to_bf16(const f32x4 (&v)[8], const float* gain, bf16_t* orow, int lane) {
;     const f32x4* gr = (const f32x4*)gain + lane;
;     float s = 0.f;
; #pragma unroll
;     for (int j = 0; j < 8; ++j) s += (v[j].x * v[j].x + v[j].y * v[j].y) + (v[j].z * v[j].z + v[j].w * v[j].w);
;     const float rstd = rsqrtf(wave_sum(s) * (1.f / D) + EPS);
;     u32x2* o8 = (u32x2*)orow + lane;
; #pragma unroll
;     for (int j = 0; j < 8; ++j) { const f32x4 g = gr[64 * j]; u32x2 w; w.x = cvt_pk_bf16(v[j].x * rstd * g.x, v[j].y * rstd * g.y); w.y = cvt_pk_bf16(v[j].z * rstd * g.z, v[j].w * rstd * g.w); o8[64 * j] = w; }
; }
; __global__ void __launch_bounds__(NTHR, 2) hybrid_fwd(Args args) {
;     ...
;         for (int m = gw; m < M; m += NGW) {
;             const int mn = m + NGW < M ? m + NGW : m;
;             const float* xrow = (mn < MP) ? args.in[I_XP] + (size_t)mn * D : args.in[I_XS] + (size_t)(mn - MP) * D;
;             f32x4 xn[8];
; #pragma unroll
;             for (int j = 0; j < 8; ++j) xn[j] = __builtin_nontemporal_load(&((const f32x4*)xrow + lane)[64 * j]);
;             rms_row_to_bf16(xv, args.in[I_F1PRE], XN + (size_t)m * D, lane);
; #pragma unroll
;             for (int j = 0; j < 8; ++j) xv[j] = xn[j];
;             const float* prow = (m < MP) ? args.in[I_PP] + (size_t)m * PLE : args.in[I_PS] + (size_t)(m - MP) * PLE;
;             const f32x4 pv = __builtin_nontemporal_load(&((const f32x4*)prow)[lane]); u32x2 w; w.x = cvt_pk_bf16(pv.x, pv.y); w.y = cvt_pk_bf16(pv.z, pv.w);
;             ((u32x2*)(PB + (size_t)m * PLE))[lane] = w;
	v_add_f32_e32 v64, v64, v66
	ds_bpermute_b32 v66, v65, v64
	s_cselect_b32 s31, s31, 0
	s_cselect_b32 s30, s29, s30
	s_cselect_b32 s29, s9, s11
	s_cselect_b32 s33, s8, s10
	s_waitcnt lgkmcnt(0)
	v_add_f32_e32 v64, v64, v66
	ds_bpermute_b32 v66, v67, v64
	s_lshl_b64 s[30:31], s[30:31], 13
	s_add_u32 s30, s33, s30
	s_addc_u32 s31, s29, s31
	v_lshl_add_u64 v[84:85], s[30:31], 0, v[34:35]
	s_waitcnt lgkmcnt(0)
	v_add_f32_e32 v64, v64, v66
	ds_bpermute_b32 v66, v69, v64
	v_add_co_u32_e32 v90, vcc, s22, v84
	global_load_dwordx4 v[48:51], v34, s[30:31] nt
	global_load_dwordx4 v[52:55], v34, s[30:31] offset:1024 nt
	global_load_dwordx4 v[56:59], v34, s[30:31] offset:2048 nt
	global_load_dwordx4 v[60:63], v34, s[30:31] offset:3072 nt
	v_addc_co_u32_e32 v91, vcc, 0, v85, vcc
	s_waitcnt lgkmcnt(0)
	v_add_f32_e32 v64, v64, v66
	ds_bpermute_b32 v66, v71, v64
	global_load_dwordx4 v[78:81], v[90:91], off nt
	global_load_dwordx4 v[82:85], v[90:91], off offset:1024 nt
	global_load_dwordx4 v[86:89], v[90:91], off offset:2048 nt
	s_nop 0
	global_load_dwordx4 v[90:93], v[90:91], off offset:3072 nt
	s_add_u32 s29, s74, s20
	s_addc_u32 s30, s75, s21
	s_add_i32 s33, s25, 0xffff8000
	s_waitcnt lgkmcnt(0)
	v_add_f32_e32 v64, v64, v66
	ds_bpermute_b32 v66, v72, v64
	s_cmp_lt_i32 s25, 0x8000
	s_cselect_b32 s31, s30, 0
	s_cselect_b32 s30, s29, s33
	s_cselect_b32 s25, s13, s15
	s_waitcnt lgkmcnt(0)
	v_add_f32_e32 v64, v64, v66
	v_fmamk_f32 v64, v64, 0x3a000000, v73
	v_mul_f32_e32 v66, 0x4b800000, v64
	v_cmp_gt_f32_e32 vcc, s23, v64
	s_cselect_b32 s29, s12, s14
	s_lshl_b64 s[30:31], s[30:31], 10
	v_cndmask_b32_e32 v64, v64, v66, vcc
	v_rsq_f32_e32 v64, v64
	s_add_u32 s30, s29, s30
	s_addc_u32 s31, s25, s31
	s_add_u32 s20, s20, s72
	v_mul_f32_e32 v66, 0x45800000, v64
	v_cndmask_b32_e32 v64, v64, v66, vcc
	v_pk_mul_f32 v[30:31], v[30:31], v[64:65] op_sel_hi:[1,0]
	v_pk_mul_f32 v[32:33], v[32:33], v[64:65] op_sel_hi:[1,0]
	s_waitcnt vmcnt(15)
	v_pk_mul_f32 v[30:31], v[132:133], v[30:31]
	v_pk_mul_f32 v[32:33], v[134:135], v[32:33]
	v_cvt_pk_bf16_f32 v30, v30, v31
	v_cvt_pk_bf16_f32 v31, v32, v33
	global_store_dwordx2 v[94:95], v[30:31], off
	s_nop 0
	v_pk_mul_f32 v[26:27], v[26:27], v[64:65] op_sel_hi:[1,0]
	v_pk_mul_f32 v[28:29], v[28:29], v[64:65] op_sel_hi:[1,0]
	v_pk_mul_f32 v[18:19], v[18:19], v[64:65] op_sel_hi:[1,0]
	v_pk_mul_f32 v[20:21], v[20:21], v[64:65] op_sel_hi:[1,0]
	v_pk_mul_f32 v[10:11], v[10:11], v[64:65] op_sel_hi:[1,0]
	v_pk_mul_f32 v[12:13], v[12:13], v[64:65] op_sel_hi:[1,0]
	v_pk_mul_f32 v[14:15], v[14:15], v[64:65] op_sel_hi:[1,0]
	v_pk_mul_f32 v[16:17], v[16:17], v[64:65] op_sel_hi:[1,0]
	v_pk_mul_f32 v[6:7], v[6:7], v[64:65] op_sel_hi:[1,0]
	v_pk_mul_f32 v[8:9], v[8:9], v[64:65] op_sel_hi:[1,0]
	v_pk_mul_f32 v[2:3], v[2:3], v[64:65] op_sel_hi:[1,0]
	v_pk_mul_f32 v[4:5], v[4:5], v[64:65] op_sel_hi:[1,0]
	s_addc_u32 s21, s21, s73
	s_mov_b32 s25, s28
	s_waitcnt vmcnt(15)
	v_pk_mul_f32 v[26:27], v[136:137], v[26:27]
	v_pk_mul_f32 v[28:29], v[138:139], v[28:29]
	v_cvt_pk_bf16_f32 v26, v26, v27
	v_cvt_pk_bf16_f32 v27, v28, v29
	global_store_dwordx2 v[94:95], v[26:27], off offset:512
	s_nop 0
	s_waitcnt vmcnt(9)
	v_mov_b32_e32 v30, v48
	v_mov_b32_e32 v31, v49
	v_mov_b32_e32 v32, v50
	v_mov_b32_e32 v33, v51
	v_pk_mul_f32 v[18:19], v[140:141], v[18:19]
	v_pk_mul_f32 v[20:21], v[142:143], v[20:21]
	v_cvt_pk_bf16_f32 v18, v18, v19
	v_cvt_pk_bf16_f32 v19, v20, v21
	global_store_dwordx2 v[94:95], v[18:19], off offset:1024
	s_nop 0
	s_waitcnt vmcnt(9)
	v_mov_b32_e32 v26, v52
	v_mov_b32_e32 v27, v53
	v_mov_b32_e32 v28, v54
	v_mov_b32_e32 v29, v55
	v_pk_mul_f32 v[10:11], v[144:145], v[10:11]
	v_pk_mul_f32 v[12:13], v[146:147], v[12:13]
	v_cvt_pk_bf16_f32 v10, v10, v11
	v_cvt_pk_bf16_f32 v11, v12, v13
	global_store_dwordx2 v[94:95], v[10:11], off offset:1536
	s_nop 0
	v_pk_mul_f32 v[18:19], v[22:23], v[64:65] op_sel_hi:[1,0]
	v_pk_mul_f32 v[20:21], v[24:25], v[64:65] op_sel_hi:[1,0]
	s_waitcnt vmcnt(7)
	v_mov_b32_e32 v22, v78
	v_mov_b32_e32 v23, v79
	v_mov_b32_e32 v24, v80
	v_mov_b32_e32 v25, v81
	v_pk_mul_f32 v[10:11], v[148:149], v[18:19]
	v_pk_mul_f32 v[12:13], v[150:151], v[20:21]
	v_cvt_pk_bf16_f32 v10, v10, v11
	v_cvt_pk_bf16_f32 v11, v12, v13
	global_store_dwordx2 v[94:95], v[10:11], off offset:2048
	s_nop 0
	v_mov_b32_e32 v18, v56
	v_mov_b32_e32 v19, v57
	v_mov_b32_e32 v20, v58
	v_mov_b32_e32 v21, v59
	v_pk_mul_f32 v[10:11], v[14:15], v[152:153]
	v_pk_mul_f32 v[12:13], v[16:17], v[154:155]
	v_cvt_pk_bf16_f32 v10, v10, v11
	v_cvt_pk_bf16_f32 v11, v12, v13
	global_store_dwordx2 v[94:95], v[10:11], off offset:2560
	s_nop 0
	s_waitcnt vmcnt(8)
	v_mov_b32_e32 v14, v82
	v_mov_b32_e32 v15, v83
	v_mov_b32_e32 v16, v84
	v_mov_b32_e32 v17, v85
	v_pk_mul_f32 v[6:7], v[6:7], v[156:157]
	v_pk_mul_f32 v[8:9], v[8:9], v[158:159]
	v_cvt_pk_bf16_f32 v6, v6, v7
	v_cvt_pk_bf16_f32 v7, v8, v9
	global_store_dwordx2 v[94:95], v[6:7], off offset:3072
	s_nop 0
	v_mov_b32_e32 v10, v60
	v_mov_b32_e32 v11, v61
	v_mov_b32_e32 v12, v62
	v_mov_b32_e32 v13, v63
	v_pk_mul_f32 v[2:3], v[2:3], v[160:161]
	v_pk_mul_f32 v[4:5], v[4:5], v[162:163]
	v_cvt_pk_bf16_f32 v2, v2, v3
	v_cvt_pk_bf16_f32 v3, v4, v5
	global_store_dwordx2 v[94:95], v[2:3], off offset:3584
	global_load_dwordx4 v[74:77], v34, s[30:31] nt
	v_lshl_add_u64 v[94:95], s[4:5], 0, v[46:47]
	s_add_u32 s4, s4, s6
	s_addc_u32 s5, s5, s7
	s_add_u32 s16, s16, s18
	s_addc_u32 s17, s17, s19
	s_cmp_gt_i32 s28, 0x87ff
	s_waitcnt vmcnt(10)
	v_mov_b32_e32 v6, v86
	v_mov_b32_e32 v7, v87
	v_mov_b32_e32 v8, v88
	v_mov_b32_e32 v9, v89
	s_waitcnt vmcnt(9)
	v_mov_b32_e32 v2, v90
	v_mov_b32_e32 v3, v91
	v_mov_b32_e32 v4, v92
	v_mov_b32_e32 v5, v93
	s_waitcnt vmcnt(0)
	v_cvt_pk_bf16_f32 v48, v74, v75
	v_cvt_pk_bf16_f32 v49, v76, v77
	global_store_dwordx2 v[94:95], v[48:49], off
	s_cbranch_scc0 .LBB0_21

; __device__ __forceinline__ unsigned cvt_pk_bf16(float lo, float hi) { const f32x2_cv v = {lo, hi}; return __builtin_bit_cast(unsigned, __builtin_convertvector(v, bf16x2_cv)); }
; __device__ __forceinline__ float bf_lo(unsigned u) { return __uint_as_float(u << 16); }
; __device__ __forceinline__ float bf_hi(unsigned u) { return __uint_as_float(u & 0xffff0000u); }
; template <bool XIN_BF, bool XOUT_BF>
; __device__ __forceinline__ void norm_pass(const float* xp, const float* xs, const bf16_t* xbin, const bf16_t* Y, const float* post, float scale, const float* pre, float* X, bf16_t* xbout, bf16_t* XN, int gw, int NGW, int lane, const float* PART = nullptr) {
;     f32x4 v[8]; u32x2 y[8];
;     norm_load_x<XIN_BF, XOUT_BF>(xp, xs, xbin, gw, lane, v); norm_load_y(Y, PART, gw, lane, y);
;     for (int m = gw; m < M; m += NGW) {
;         f32x4 vn[8]; u32x2 yn[8];
;         const int mn = m + NGW < M ? m + NGW : m;
;         norm_load_x<XIN_BF, XOUT_BF>(xp, xs, xbin, mn, lane, vn); norm_load_y(Y, PART, mn, lane, yn);
;     ...
;         const float rs = rsqrtf(wave_sum(s) * (1.f / D) + EPS) * scale; float s2 = 0.f;
; #pragma unroll
;         for (int j = 0; j < 8; ++j) { const f32x4 g = ((const f32x4*)post + lane)[64 * j];
;             v[j].x += bf_lo(y[j].x) * rs * g.x; v[j].y += bf_hi(y[j].x) * rs * g.y; v[j].z += bf_lo(y[j].y) * rs * g.z; v[j].w += bf_hi(y[j].y) * rs * g.w;
;             s2 += (v[j].x * v[j].x + v[j].y * v[j].y) + (v[j].z * v[j].z + v[j].w * v[j].w);
;             if (XOUT_BF) { u32x2 w; w.x = cvt_pk_bf16(v[j].x, v[j].y); w.y = cvt_pk_bf16(v[j].z, v[j].w); __builtin_nontemporal_store(w, &((u32x2*)(xbout + (size_t)m * D) + lane)[64 * j]); }
;             else __builtin_nontemporal_store(v[j], &((f32x4*)(X + (size_t)m * D) + lane)[64 * j]); }
;         if (pre) {
;             const float r2 = rsqrtf(wave_sum(s2) * (1.f / D) + EPS); u32x2* o8 = (u32x2*)(XN + (size_t)m * D) + lane;
; #pragma unroll
;             for (int j = 0; j < 8; ++j) { const f32x4 g = ((const f32x4*)pre + lane)[64 * j]; u32x2 w; w.x = cvt_pk_bf16(v[j].x * r2 * g.x, v[j].y * r2 * g.y); w.y = cvt_pk_bf16(v[j].z * r2 * g.z, v[j].w * r2 * g.w); o8[64 * j] = w; }
.LBB0_256:
	s_cmp_gt_i32 s74, 0x87ff
	s_cbranch_scc1 .LBB0_292
	v_mbcnt_lo_u32_b32 v33, -1, 0
	v_mbcnt_hi_u32_b32 v33, -1, v33
	v_and_b32_e32 v34, 64, v33
	v_add_u32_e32 v34, 64, v34
	v_xor_b32_e32 v35, 1, v33
	v_cmp_lt_i32_e32 vcc, v35, v34
	s_load_dwordx2 s[4:5], s[42:43], 0x48
	s_load_dwordx2 s[6:7], s[42:43], 0x68
	v_cndmask_b32_e32 v35, v33, v35, vcc
	v_lshlrev_b32_e32 v124, 2, v35
	v_xor_b32_e32 v35, 2, v33
	v_cmp_lt_i32_e32 vcc, v35, v34
	v_mov_b32_e32 v71, 0
	v_mov_b32_e32 v65, v71
	v_cndmask_b32_e32 v35, v33, v35, vcc
	v_lshlrev_b32_e32 v125, 2, v35
	v_xor_b32_e32 v35, 4, v33
	v_cmp_lt_i32_e32 vcc, v35, v34
	s_waitcnt lgkmcnt(0)
	v_lshl_add_u64 v[78:79], s[4:5], 0, v[64:65]
	s_cmp_lg_u64 s[6:7], 0
	v_cndmask_b32_e32 v35, v33, v35, vcc
	v_lshlrev_b32_e32 v126, 2, v35
	v_xor_b32_e32 v35, 8, v33
	v_cmp_lt_i32_e32 vcc, v35, v34
	v_lshl_add_u64 v[80:81], s[6:7], 0, v[64:65]
	s_mov_b64 s[12:13], 0x1400
	v_cndmask_b32_e32 v35, v33, v35, vcc
	v_lshlrev_b32_e32 v127, 2, v35
	v_xor_b32_e32 v35, 16, v33
	v_cmp_lt_i32_e32 vcc, v35, v34
	s_cselect_b64 s[4:5], -1, 0
	v_lshl_add_u64 v[84:85], v[78:79], 0, s[12:13]
	v_cndmask_b32_e32 v35, v33, v35, vcc
	v_lshl_add_u64 v[94:95], v[80:81], 0, s[12:13]
	s_add_u32 s12, s84, s16
	v_lshlrev_b32_e32 v130, 2, v35
	v_xor_b32_e32 v35, 32, v33
	s_mov_b64 s[14:15], 0x1800
	s_addc_u32 s13, s85, s17
	s_ashr_i32 s73, s72, 31
	v_cmp_lt_i32_e32 vcc, v35, v34
	v_lshl_add_u64 v[86:87], v[78:79], 0, s[14:15]
	v_lshl_add_u64 v[96:97], v[80:81], 0, s[14:15]
	s_lshl_b64 s[14:15], s[72:73], 12
	v_mov_b32_e32 v67, v71
	v_lshlrev_b32_e32 v32, 2, v128
	v_cndmask_b32_e32 v33, v33, v35, vcc
	s_mov_b64 s[6:7], 0x1000
	s_mov_b64 s[18:19], 0x1c00
	s_add_u32 s16, s86, s16
	v_lshl_add_u64 v[74:75], s[94:95], 0, v[66:67]
	s_mov_b32 s3, 0
	v_lshlrev_b32_e32 v131, 2, v33
	v_lshl_add_u64 v[82:83], v[78:79], 0, s[6:7]
	v_lshl_add_u64 v[90:91], v[78:79], 0, s[18:19]
	v_lshl_add_u64 v[92:93], v[80:81], 0, s[6:7]
	v_lshl_add_u64 v[98:99], v[80:81], 0, s[18:19]
	s_addc_u32 s17, s87, s17
	s_movk_i32 s22, 0x1000
	v_lshlrev_b32_e32 v70, 2, v32
	s_mov_b32 s23, 0x40000
	v_mov_b32_e32 v132, 0x358637bd
	s_mov_b32 s24, 0x800000
	s_mov_b32 s25, 0xad00000
	s_mov_b32 s26, s74
	global_load_dwordx4 v[168:171], v[78:79], off
	global_load_dwordx4 v[172:175], v[78:79], off offset:1024
	global_load_dwordx4 v[176:179], v[78:79], off offset:2048
	global_load_dwordx4 v[180:183], v[78:79], off offset:3072
	global_load_dwordx4 v[184:187], v[82:83], off
	global_load_dwordx4 v[188:191], v[84:85], off
	global_load_dwordx4 v[192:195], v[86:87], off
	global_load_dwordx4 v[196:199], v[90:91], off
	global_load_dwordx4 v[200:203], v[80:81], off
	global_load_dwordx4 v[204:207], v[80:81], off offset:1024
	global_load_dwordx4 v[208:211], v[80:81], off offset:2048
	global_load_dwordx4 v[212:215], v[80:81], off offset:3072
	global_load_dwordx4 v[216:219], v[92:93], off
	global_load_dwordx4 v[220:223], v[94:95], off
	global_load_dwordx4 v[224:227], v[96:97], off
	global_load_dwordx4 v[228:231], v[98:99], off
	s_waitcnt vmcnt(0)
	s_branch .LBB0_259
; __device__ __forceinline__ unsigned cvt_pk_bf16(float lo, float hi) { const f32x2_cv v = {lo, hi}; return __builtin_bit_cast(unsigned, __builtin_convertvector(v, bf16x2_cv)); }
; __device__ __forceinline__ void norm_load_y(const bf16_t* Y, const float* PART, int m, int lane, u32x2 (&y)[8]) {
;     const u32x2* yr = (const u32x2*)(Y + (size_t)m * D) + lane;
; #pragma unroll
;     for (int j = 0; j < 8; ++j) y[j] = __builtin_nontemporal_load(&yr[64 * j]);
;     const int pm = m >> 8, q = pm - 16;
;     if (PART && q >= 0 && (q & 15) < 8) {
;         const int pn = q >> 4, c = (q & 15) * 8 + pn;
;         const float* pa = PART + ((size_t)(2 * c) * 256 + (m & 255)) * 256 + 4 * lane;
;         const f32x4 a = *(const f32x4*)pa, b = *(const f32x4*)(pa + 65536);
;         u32x2 w; w.x = cvt_pk_bf16(a.x + b.x, a.y + b.y); w.y = cvt_pk_bf16(a.z + b.z, a.w + b.w);
; #pragma unroll
;         for (int j = 0; j < 8; ++j) if (j == pn) y[j] = w;
;     }
; }
; template <bool XIN_BF, bool XOUT_BF>
; __device__ __forceinline__ void norm_pass(const float* xp, const float* xs, const bf16_t* xbin, const bf16_t* Y, const float* post, float scale, const float* pre, float* X, bf16_t* xbout, bf16_t* XN, int gw, int NGW, int lane, const float* PART = nullptr) {
;     ...
;     for (int m = gw; m < M; m += NGW) {
;         f32x4 vn[8]; u32x2 yn[8];
;         const int mn = m + NGW < M ? m + NGW : m;
;         norm_load_x<XIN_BF, XOUT_BF>(xp, xs, xbin, mn, lane, vn); norm_load_y(Y, PART, mn, lane, yn);
;     ...
;         for (int j = 0; j < 8; ++j) { v[j] = vn[j]; y[j] = yn[j]; }
.LBB0_258:
	s_add_u32 s12, s12, s14
	s_addc_u32 s13, s13, s15
	s_add_u32 s16, s16, s14
	s_addc_u32 s17, s17, s15
	s_andn2_b64 vcc, exec, s[18:19]
	s_waitcnt vmcnt(15)
	v_mov_b64_e32 v[106:107], v[110:111]
	s_waitcnt vmcnt(14)
	v_mov_b32_e32 v104, v108
	v_mov_b32_e32 v105, v109
	s_waitcnt vmcnt(13)
	v_mov_b32_e32 v102, v112
	v_mov_b32_e32 v103, v113
	s_waitcnt vmcnt(12)
	v_mov_b32_e32 v100, v114
	v_mov_b32_e32 v101, v115
	s_waitcnt vmcnt(11)
	v_mov_b32_e32 v88, v116
	v_mov_b32_e32 v89, v117
	s_waitcnt vmcnt(10)
	v_mov_b32_e32 v76, v118
	v_mov_b32_e32 v77, v119
	s_waitcnt vmcnt(9)
	v_mov_b32_e32 v72, v120
	v_mov_b32_e32 v73, v121
	s_waitcnt vmcnt(8)
	v_mov_b32_e32 v68, v122
	v_mov_b32_e32 v69, v123
	v_mov_b32_e32 v28, v60
	v_mov_b32_e32 v29, v61
	v_mov_b32_e32 v30, v62
	v_mov_b32_e32 v31, v63
	v_mov_b32_e32 v24, v56
	v_mov_b32_e32 v25, v57
	v_mov_b32_e32 v26, v58
	v_mov_b32_e32 v27, v59
	v_mov_b32_e32 v20, v52
	v_mov_b32_e32 v21, v53
	v_mov_b32_e32 v22, v54
	v_mov_b32_e32 v23, v55
	v_mov_b32_e32 v16, v44
	v_mov_b32_e32 v17, v45
	v_mov_b32_e32 v18, v46
	v_mov_b32_e32 v19, v47
	v_mov_b32_e32 v12, v48
	v_mov_b32_e32 v13, v49
	v_mov_b32_e32 v14, v50
	v_mov_b32_e32 v15, v51
	v_mov_b32_e32 v8, v40
	v_mov_b32_e32 v9, v41
	v_mov_b32_e32 v10, v42
	v_mov_b32_e32 v11, v43
	v_mov_b32_e32 v4, v36
	v_mov_b32_e32 v5, v37
	v_mov_b32_e32 v6, v38
	v_mov_b32_e32 v7, v39
	v_mov_b32_e32 v0, v32
	v_mov_b32_e32 v1, v33
	v_mov_b32_e32 v2, v34
	v_mov_b32_e32 v3, v35
	s_cbranch_vccz .LBB0_292
.LBB0_259:
	s_mov_b32 s2, s26
	s_add_i32 s26, s26, s72
	s_cmp_gt_i32 s26, 0x87ff
	s_cselect_b64 s[18:19], -1, 0
	s_cmp_lt_i32 s26, 0x8800
	s_cselect_b32 s6, s26, s2
	s_add_i32 s2, s6, 0xffff8000
	s_ashr_i32 s7, s6, 31
	s_cmp_lt_i32 s6, 0x8000
	s_cselect_b32 s21, s7, 0
	s_cselect_b32 s20, s6, s2
	s_cselect_b32 s2, s9, s11
	s_cselect_b32 s27, s8, s10
	s_lshl_b64 s[20:21], s[20:21], 13
	s_add_u32 s20, s27, s20
	s_addc_u32 s21, s2, s21
	v_lshl_add_u64 v[32:33], s[20:21], 0, v[64:65]
	global_load_dwordx4 v[60:63], v64, s[20:21] nt
	global_load_dwordx4 v[56:59], v64, s[20:21] offset:1024 nt
	global_load_dwordx4 v[52:55], v64, s[20:21] offset:2048 nt
	global_load_dwordx4 v[44:47], v64, s[20:21] offset:3072 nt
	v_add_co_u32_e32 v32, vcc, s22, v32
	s_lshl_b64 s[20:21], s[6:7], 12
	s_nop 0
	v_addc_co_u32_e32 v33, vcc, 0, v33, vcc
	v_lshl_add_u64 v[122:123], v[74:75], 0, s[20:21]
	global_load_dwordx4 v[48:51], v[32:33], off nt
	global_load_dwordx4 v[40:43], v[32:33], off offset:1024 nt
	global_load_dwordx4 v[36:39], v[32:33], off offset:2048 nt
	s_nop 0
	global_load_dwordx4 v[32:35], v[32:33], off offset:3072 nt
	s_nop 0
	global_load_dwordx2 v[110:111], v[122:123], off nt
	global_load_dwordx2 v[108:109], v[122:123], off offset:512 nt
	global_load_dwordx2 v[112:113], v[122:123], off offset:1024 nt
	global_load_dwordx2 v[114:115], v[122:123], off offset:1536 nt
	global_load_dwordx2 v[116:117], v[122:123], off offset:2048 nt
	global_load_dwordx2 v[118:119], v[122:123], off offset:2560 nt
	global_load_dwordx2 v[120:121], v[122:123], off offset:3072 nt
	s_nop 0
	global_load_dwordx2 v[122:123], v[122:123], off offset:3584 nt
	s_ashr_i32 s2, s6, 8
	s_cmp_lt_i32 s2, 16
	s_cbranch_scc1 .LBB0_290
	s_bfe_u32 s7, s6, 0x40008
	s_cmp_gt_u32 s7, 7
	s_cbranch_scc1 .LBB0_290
	s_add_i32 s28, s2, -16
	s_lshr_b32 s27, s28, 4
	s_lshl_b32 s2, s7, 4
	s_lshl_b32 s7, s27, 1
	s_add_i32 s2, s7, s2
	s_lshl_b64 s[20:21], s[2:3], 18
	v_readlane_b32 s2, v236, 10
	s_add_u32 s2, s2, s20
	v_readlane_b32 s7, v236, 11
	s_addc_u32 s7, s7, s21
	s_lshl_b32 s6, s6, 10
	s_and_b32 s6, s6, 0x3fc00
	s_add_u32 s6, s2, s6
	s_addc_u32 s7, s7, 0
	v_lshl_add_u64 v[134:135], s[6:7], 0, v[70:71]
	v_add_co_u32_e32 v138, vcc, s23, v134
	s_cmp_lt_u32 s28, 16
	s_nop 0
	v_addc_co_u32_e32 v139, vcc, 0, v135, vcc
	global_load_dwordx4 v[134:137], v70, s[6:7]
	s_nop 0
	global_load_dwordx4 v[138:141], v[138:139], off
	s_cselect_b64 s[6:7], -1, 0
	s_cmp_lt_i32 s27, 4
	s_mov_b64 s[20:21], -1
	s_nop 0
	s_waitcnt vmcnt(0)
	v_pk_add_f32 v[136:137], v[136:137], v[140:141]
	v_pk_add_f32 v[134:135], v[134:135], v[138:139]
	s_nop 0
	v_cvt_pk_bf16_f32 v133, v134, v135
	v_cvt_pk_bf16_f32 v134, v136, v137
	s_cbranch_scc1 .LBB0_277
	s_cmp_lt_i32 s27, 6
	s_cbranch_scc1 .LBB0_270
	s_cmp_lt_i32 s27, 7
	s_cbranch_scc1 .LBB0_267
	s_cmp_eq_u32 s27, 7
	v_mov_b32_e32 v135, v123
	v_mov_b32_e32 v136, v122
	s_cbranch_scc0 .LBB0_266
	v_mov_b32_e32 v135, v134
	v_mov_b32_e32 v136, v133

; __device__ __forceinline__ unsigned cvt_pk_bf16(float lo, float hi) { const f32x2_cv v = {lo, hi}; return __builtin_bit_cast(unsigned, __builtin_convertvector(v, bf16x2_cv)); }
; __device__ __forceinline__ float bf_lo(unsigned u) { return __uint_as_float(u << 16); }
; __device__ __forceinline__ float bf_hi(unsigned u) { return __uint_as_float(u & 0xffff0000u); }
; template <bool XIN_BF, bool XOUT_BF>
; __device__ __forceinline__ void norm_pass(const float* xp, const float* xs, const bf16_t* xbin, const bf16_t* Y, const float* post, float scale, const float* pre, float* X, bf16_t* xbout, bf16_t* XN, int gw, int NGW, int lane, const float* PART = nullptr) {
;     ...
;         float s = 0.f;
; #pragma unroll
;         for (int j = 0; j < 8; ++j) { const float a = bf_lo(y[j].x), b = bf_hi(y[j].x), c = bf_lo(y[j].y), d = bf_hi(y[j].y); s += (a * a + b * b) + (c * c + d * d); }
;         const float rs = rsqrtf(wave_sum(s) * (1.f / D) + EPS) * scale; float s2 = 0.f;
; #pragma unroll
;         for (int j = 0; j < 8; ++j) { const f32x4 g = ((const f32x4*)post + lane)[64 * j];
;             v[j].x += bf_lo(y[j].x) * rs * g.x; v[j].y += bf_hi(y[j].x) * rs * g.y; v[j].z += bf_lo(y[j].y) * rs * g.z; v[j].w += bf_hi(y[j].y) * rs * g.w;
;             s2 += (v[j].x * v[j].x + v[j].y * v[j].y) + (v[j].z * v[j].z + v[j].w * v[j].w);
;             if (XOUT_BF) { u32x2 w; w.x = cvt_pk_bf16(v[j].x, v[j].y); w.y = cvt_pk_bf16(v[j].z, v[j].w); __builtin_nontemporal_store(w, &((u32x2*)(xbout + (size_t)m * D) + lane)[64 * j]); }
;             else __builtin_nontemporal_store(v[j], &((f32x4*)(X + (size_t)m * D) + lane)[64 * j]); }
.LBB0_290:
	s_nop 0
	s_nop 0
	v_lshlrev_b32_e32 v138, 16, v107
	v_and_b32_e32 v139, 0xffff0000, v107
	v_and_b32_e32 v107, 0xffff0000, v105
	v_lshlrev_b32_e32 v140, 16, v106
	v_and_b32_e32 v141, 0xffff0000, v106
	v_lshlrev_b32_e32 v106, 16, v105
	v_and_b32_e32 v143, 0xffff0000, v104
	v_mov_b32_e32 v144, v139
	v_mov_b32_e32 v145, v107
	v_lshlrev_b32_e32 v142, 16, v104
	v_mov_b32_e32 v104, v138
	v_mov_b32_e32 v105, v106
	v_pk_mul_f32 v[144:145], v[144:145], v[144:145]
	v_mov_b32_e32 v146, v141
	v_mov_b32_e32 v147, v143
	v_pk_fma_f32 v[104:105], v[104:105], v[104:105], v[144:145]
	v_mov_b32_e32 v144, v140
	v_mov_b32_e32 v145, v142
	v_pk_mul_f32 v[146:147], v[146:147], v[146:147]
	v_and_b32_e32 v153, 0xffff0000, v100
	v_pk_fma_f32 v[144:145], v[144:145], v[144:145], v[146:147]
	v_and_b32_e32 v147, 0xffff0000, v102
	v_pk_add_f32 v[104:105], v[144:145], v[104:105]
	v_and_b32_e32 v145, 0xffff0000, v103
	v_lshlrev_b32_e32 v144, 16, v103
	v_lshlrev_b32_e32 v146, 16, v102
	v_mov_b32_e32 v148, v147
	v_mov_b32_e32 v149, v145
	v_mov_b32_e32 v102, v146
	v_mov_b32_e32 v103, v144
	v_pk_mul_f32 v[148:149], v[148:149], v[148:149]
	v_lshlrev_b32_e32 v152, 16, v100
	v_pk_fma_f32 v[102:103], v[102:103], v[102:103], v[148:149]
	v_and_b32_e32 v149, 0xffff0000, v101
	v_lshlrev_b32_e32 v148, 16, v101
	v_mul_f32_e32 v150, v149, v149
	v_mul_f32_e32 v100, v153, v153
	v_lshlrev_b32_e32 v154, 16, v89
	v_and_b32_e32 v155, 0xffff0000, v89
	v_lshlrev_b32_e32 v158, 16, v88
	v_and_b32_e32 v159, 0xffff0000, v88
	v_pk_add_f32 v[104:105], v[104:105], v[104:105] op_sel:[0,1] op_sel_hi:[1,0]
	v_pk_add_f32 v[102:103], v[102:103], v[102:103] op_sel:[0,1] op_sel_hi:[1,0]
	v_pk_fma_f32 v[150:151], v[148:149], v[148:149], v[150:151] op_sel_hi:[1,1,0]
	v_pk_fma_f32 v[100:101], v[152:153], v[152:153], v[100:101] op_sel_hi:[1,1,0]
	v_pk_mul_f32 v[156:157], v[154:155], v[154:155]
	v_pk_mul_f32 v[88:89], v[158:159], v[158:159]
	v_mov_b32_e32 v101, v156
	v_mov_b32_e32 v151, v157
	v_mov_b32_e32 v105, v88
	v_mov_b32_e32 v103, v89
	v_pk_add_f32 v[100:101], v[100:101], v[150:151]
	v_pk_add_f32 v[88:89], v[104:105], v[102:103]
	v_and_b32_e32 v105, 0xffff0000, v77
	v_and_b32_e32 v151, 0xffff0000, v76
	v_pk_add_f32 v[88:89], v[88:89], v[100:101]
	v_lshlrev_b32_e32 v104, 16, v77
	v_lshlrev_b32_e32 v150, 16, v76
	v_mov_b32_e32 v100, v151
	v_mov_b32_e32 v101, v105
	v_mov_b32_e32 v76, v150
	v_mov_b32_e32 v77, v104
	v_pk_mul_f32 v[100:101], v[100:101], v[100:101]
	v_and_b32_e32 v157, 0xffff0000, v73
	v_and_b32_e32 v161, 0xffff0000, v72
	v_pk_fma_f32 v[76:77], v[76:77], v[76:77], v[100:101]
	v_lshlrev_b32_e32 v156, 16, v73
	v_mul_f32_e32 v100, v157, v157
	v_lshlrev_b32_e32 v160, 16, v72
	v_mul_f32_e32 v72, v161, v161
	v_lshlrev_b32_e32 v162, 16, v69
	v_and_b32_e32 v163, 0xffff0000, v69
	v_lshlrev_b32_e32 v164, 16, v68
	v_and_b32_e32 v165, 0xffff0000, v68
	v_pk_add_f32 v[88:89], v[88:89], v[88:89] op_sel:[0,1] op_sel_hi:[1,0]
	v_pk_add_f32 v[76:77], v[76:77], v[76:77] op_sel:[0,1] op_sel_hi:[1,0]
	v_pk_fma_f32 v[100:101], v[156:157], v[156:157], v[100:101] op_sel_hi:[1,1,0]
	v_pk_fma_f32 v[72:73], v[160:161], v[160:161], v[72:73] op_sel_hi:[1,1,0]
	v_pk_mul_f32 v[102:103], v[162:163], v[162:163]
	v_pk_mul_f32 v[68:69], v[164:165], v[164:165]
	v_mov_b32_e32 v73, v102
	v_mov_b32_e32 v101, v103
	v_mov_b32_e32 v89, v68
	v_mov_b32_e32 v77, v69
	v_pk_add_f32 v[72:73], v[72:73], v[100:101]
	v_pk_add_f32 v[68:69], v[88:89], v[76:77]
	s_nop 0
	v_pk_add_f32 v[68:69], v[68:69], v[72:73]
	v_lshl_add_u64 v[72:73], s[12:13], 0, v[66:67]
	v_add_f32_e32 v68, v68, v69
	ds_bpermute_b32 v69, v124, v68
	s_waitcnt lgkmcnt(0)
	v_add_f32_e32 v68, v68, v69
	ds_bpermute_b32 v69, v125, v68
	s_waitcnt lgkmcnt(0)
	v_add_f32_e32 v68, v68, v69
	ds_bpermute_b32 v69, v126, v68
	s_waitcnt lgkmcnt(0)
	v_add_f32_e32 v68, v68, v69
	ds_bpermute_b32 v69, v127, v68
	s_waitcnt lgkmcnt(0)
	v_add_f32_e32 v68, v68, v69
	ds_bpermute_b32 v69, v130, v68
	s_waitcnt lgkmcnt(0)
	v_add_f32_e32 v68, v68, v69
	ds_bpermute_b32 v69, v131, v68
	s_waitcnt lgkmcnt(0)
	v_add_f32_e32 v68, v68, v69
	v_fmamk_f32 v68, v68, 0x3a000000, v132
	v_mul_f32_e32 v69, 0x4b800000, v68
	v_cmp_gt_f32_e32 vcc, s24, v68
	s_nop 1
	v_cndmask_b32_e32 v68, v68, v69, vcc
	v_rsq_f32_e32 v68, v68
	s_nop 0
	v_mul_f32_e32 v69, 0x45800000, v68
	v_cndmask_b32_e32 v68, v68, v69, vcc
	v_mul_f32_e32 v76, 0.5, v68
	v_pk_mul_f32 v[68:69], v[76:77], v[140:141] op_sel_hi:[0,1]
	v_pk_fma_f32 v[68:69], v[168:169], v[68:69], v[28:29]
	v_pk_mul_f32 v[28:29], v[76:77], v[138:139] op_sel_hi:[0,1]
	v_pk_fma_f32 v[28:29], v[170:171], v[28:29], v[30:31]
	v_cvt_pk_bf16_f32 v30, v68, v69
	v_cvt_pk_bf16_f32 v31, v28, v29
	global_store_dwordx2 v[72:73], v[30:31], off nt
	s_nop 0
	v_pk_mul_f32 v[30:31], v[76:77], v[142:143] op_sel_hi:[0,1]
	v_pk_mul_f32 v[88:89], v[76:77], v[106:107] op_sel_hi:[0,1]
	s_andn2_b64 vcc, exec, s[4:5]
	s_nop 0
	v_pk_fma_f32 v[24:25], v[172:173], v[30:31], v[24:25]
	v_pk_fma_f32 v[26:27], v[174:175], v[88:89], v[26:27]
	v_cvt_pk_bf16_f32 v30, v24, v25
	v_cvt_pk_bf16_f32 v31, v26, v27
	global_store_dwordx2 v[72:73], v[30:31], off offset:512 nt
	s_nop 0
	v_pk_mul_f32 v[30:31], v[76:77], v[146:147] op_sel_hi:[0,1]
	v_pk_mul_f32 v[88:89], v[76:77], v[144:145] op_sel_hi:[0,1]
	s_nop 0
	v_pk_fma_f32 v[20:21], v[176:177], v[30:31], v[20:21]
	v_pk_fma_f32 v[22:23], v[178:179], v[88:89], v[22:23]
	v_cvt_pk_bf16_f32 v30, v20, v21
	v_cvt_pk_bf16_f32 v31, v22, v23
	global_store_dwordx2 v[72:73], v[30:31], off offset:1024 nt
	s_nop 0
	v_pk_mul_f32 v[30:31], v[76:77], v[152:153] op_sel_hi:[0,1]
	v_pk_mul_f32 v[88:89], v[76:77], v[148:149] op_sel_hi:[0,1]
	s_nop 0
	v_pk_fma_f32 v[16:17], v[180:181], v[30:31], v[16:17]
; __device__ __forceinline__ unsigned cvt_pk_bf16(float lo, float hi) { const f32x2_cv v = {lo, hi}; return __builtin_bit_cast(unsigned, __builtin_convertvector(v, bf16x2_cv)); }
; __device__ __forceinline__ float bf_lo(unsigned u) { return __uint_as_float(u << 16); }
; __device__ __forceinline__ float bf_hi(unsigned u) { return __uint_as_float(u & 0xffff0000u); }
; template <bool XIN_BF, bool XOUT_BF>
; __device__ __forceinline__ void norm_pass(const float* xp, const float* xs, const bf16_t* xbin, const bf16_t* Y, const float* post, float scale, const float* pre, float* X, bf16_t* xbout, bf16_t* XN, int gw, int NGW, int lane, const float* PART = nullptr) {
;     ...
;         for (int j = 0; j < 8; ++j) { const f32x4 g = ((const f32x4*)post + lane)[64 * j];
;             v[j].x += bf_lo(y[j].x) * rs * g.x; v[j].y += bf_hi(y[j].x) * rs * g.y; v[j].z += bf_lo(y[j].y) * rs * g.z; v[j].w += bf_hi(y[j].y) * rs * g.w;
;             s2 += (v[j].x * v[j].x + v[j].y * v[j].y) + (v[j].z * v[j].z + v[j].w * v[j].w);
;             if (XOUT_BF) { u32x2 w; w.x = cvt_pk_bf16(v[j].x, v[j].y); w.y = cvt_pk_bf16(v[j].z, v[j].w); __builtin_nontemporal_store(w, &((u32x2*)(xbout + (size_t)m * D) + lane)[64 * j]); }
;             else __builtin_nontemporal_store(v[j], &((f32x4*)(X + (size_t)m * D) + lane)[64 * j]); }
	v_pk_fma_f32 v[18:19], v[182:183], v[88:89], v[18:19]
	v_cvt_pk_bf16_f32 v30, v16, v17
	v_cvt_pk_bf16_f32 v31, v18, v19
	global_store_dwordx2 v[72:73], v[30:31], off offset:1536 nt
	s_nop 0
	v_pk_mul_f32 v[30:31], v[76:77], v[158:159] op_sel_hi:[0,1]
	v_pk_mul_f32 v[88:89], v[76:77], v[154:155] op_sel_hi:[0,1]
	s_nop 0
	v_pk_fma_f32 v[12:13], v[184:185], v[30:31], v[12:13]
	v_pk_fma_f32 v[14:15], v[186:187], v[88:89], v[14:15]
	v_cvt_pk_bf16_f32 v30, v12, v13
	v_cvt_pk_bf16_f32 v31, v14, v15
	global_store_dwordx2 v[72:73], v[30:31], off offset:2048 nt
	s_nop 0
	v_pk_mul_f32 v[30:31], v[76:77], v[150:151] op_sel_hi:[0,1]
	v_pk_mul_f32 v[88:89], v[76:77], v[104:105] op_sel_hi:[0,1]
	s_nop 0
	v_pk_fma_f32 v[8:9], v[30:31], v[188:189], v[8:9]
	v_pk_fma_f32 v[10:11], v[88:89], v[190:191], v[10:11]
	v_cvt_pk_bf16_f32 v30, v8, v9
	v_cvt_pk_bf16_f32 v31, v10, v11
	global_store_dwordx2 v[72:73], v[30:31], off offset:2560 nt
	s_nop 0
	v_pk_mul_f32 v[30:31], v[76:77], v[160:161] op_sel_hi:[0,1]
	v_pk_mul_f32 v[88:89], v[76:77], v[156:157] op_sel_hi:[0,1]
	s_nop 0
	v_pk_fma_f32 v[4:5], v[30:31], v[192:193], v[4:5]
	v_pk_fma_f32 v[6:7], v[88:89], v[194:195], v[6:7]
	v_cvt_pk_bf16_f32 v30, v4, v5
	v_cvt_pk_bf16_f32 v31, v6, v7
	global_store_dwordx2 v[72:73], v[30:31], off offset:3072 nt
	s_nop 0
	v_pk_mul_f32 v[30:31], v[76:77], v[164:165] op_sel_hi:[0,1]
	v_pk_mul_f32 v[76:77], v[76:77], v[162:163] op_sel_hi:[0,1]
	s_nop 0
	v_pk_fma_f32 v[30:31], v[30:31], v[196:197], v[0:1]
	v_pk_fma_f32 v[0:1], v[76:77], v[198:199], v[2:3]
	v_cvt_pk_bf16_f32 v2, v30, v31
	v_cvt_pk_bf16_f32 v3, v0, v1
	global_store_dwordx2 v[72:73], v[2:3], off offset:3584 nt
	s_cbranch_vccnz .LBB0_258
; __device__ __forceinline__ unsigned cvt_pk_bf16(float lo, float hi) { const f32x2_cv v = {lo, hi}; return __builtin_bit_cast(unsigned, __builtin_convertvector(v, bf16x2_cv)); }
; template <bool XIN_BF, bool XOUT_BF>
; __device__ __forceinline__ void norm_pass(const float* xp, const float* xs, const bf16_t* xbin, const bf16_t* Y, const float* post, float scale, const float* pre, float* X, bf16_t* xbout, bf16_t* XN, int gw, int NGW, int lane, const float* PART = nullptr) {
;     ...
;             s2 += (v[j].x * v[j].x + v[j].y * v[j].y) + (v[j].z * v[j].z + v[j].w * v[j].w);
;             if (XOUT_BF) { u32x2 w; w.x = cvt_pk_bf16(v[j].x, v[j].y); w.y = cvt_pk_bf16(v[j].z, v[j].w); __builtin_nontemporal_store(w, &((u32x2*)(xbout + (size_t)m * D) + lane)[64 * j]); }
;             else __builtin_nontemporal_store(v[j], &((f32x4*)(X + (size_t)m * D) + lane)[64 * j]); }
;         if (pre) {
;             const float r2 = rsqrtf(wave_sum(s2) * (1.f / D) + EPS); u32x2* o8 = (u32x2*)(XN + (size_t)m * D) + lane;
; #pragma unroll
;             for (int j = 0; j < 8; ++j) { const f32x4 g = ((const f32x4*)pre + lane)[64 * j]; u32x2 w; w.x = cvt_pk_bf16(v[j].x * r2 * g.x, v[j].y * r2 * g.y); w.y = cvt_pk_bf16(v[j].z * r2 * g.z, v[j].w * r2 * g.w); o8[64 * j] = w; }
;         }
	s_nop 0
	v_mov_b32_e32 v72, v69
	v_mov_b32_e32 v73, v25
	v_mov_b32_e32 v2, v68
	v_mov_b32_e32 v3, v24
	v_pk_mul_f32 v[72:73], v[72:73], v[72:73]
	v_mov_b32_e32 v76, v28
	v_mov_b32_e32 v77, v26
	v_pk_fma_f32 v[2:3], v[2:3], v[2:3], v[72:73]
	v_mov_b32_e32 v72, v29
	v_mov_b32_e32 v73, v27
	v_pk_mul_f32 v[76:77], v[76:77], v[76:77]
	v_pk_mul_f32 v[104:105], v[12:13], v[12:13]
	v_pk_fma_f32 v[72:73], v[72:73], v[72:73], v[76:77]
	v_pk_mov_b32 v[76:77], v[20:21], v[22:23] op_sel:[1,0]
	v_pk_add_f32 v[2:3], v[2:3], v[72:73]
	v_mov_b32_e32 v72, v20
	v_pk_add_f32 v[2:3], v[2:3], v[2:3] op_sel_hi:[0,1]
	v_mov_b32_e32 v73, v23
	v_pk_mul_f32 v[76:77], v[76:77], v[76:77]
	v_mul_f32_e32 v2, v16, v16
	v_pk_fma_f32 v[72:73], v[72:73], v[72:73], v[76:77]
	v_pk_fma_f32 v[76:77], v[16:17], v[16:17], v[2:3] op_sel_hi:[1,1,0]
	v_mul_f32_e32 v2, v18, v18
	v_pk_add_f32 v[72:73], v[72:73], v[72:73] op_sel_hi:[0,1]
	v_pk_fma_f32 v[88:89], v[18:19], v[18:19], v[2:3] op_sel_hi:[1,1,0]
	v_pk_mul_f32 v[106:107], v[14:15], v[14:15]
	v_mov_b32_e32 v76, v104
	v_mov_b32_e32 v88, v105
	v_mov_b32_e32 v72, v107
	v_mov_b32_e32 v107, v3
	v_pk_add_f32 v[76:77], v[76:77], v[88:89]
	v_pk_add_f32 v[2:3], v[72:73], v[106:107]
	v_mov_b32_e32 v72, v8
	v_pk_add_f32 v[2:3], v[76:77], v[2:3]
	v_pk_mov_b32 v[76:77], v[8:9], v[10:11] op_sel:[1,0]
	v_pk_add_f32 v[2:3], v[2:3], v[2:3] op_sel_hi:[0,1]
	v_mov_b32_e32 v73, v11
	v_pk_mul_f32 v[76:77], v[76:77], v[76:77]
	v_mul_f32_e32 v2, v4, v4
	v_pk_fma_f32 v[72:73], v[72:73], v[72:73], v[76:77]
	v_pk_fma_f32 v[76:77], v[4:5], v[4:5], v[2:3] op_sel_hi:[1,1,0]
	v_mul_f32_e32 v2, v6, v6
	v_pk_add_f32 v[72:73], v[72:73], v[72:73] op_sel_hi:[0,1]
	v_pk_fma_f32 v[88:89], v[6:7], v[6:7], v[2:3] op_sel_hi:[1,1,0]
	v_pk_mul_f32 v[104:105], v[30:31], v[30:31]
	v_pk_mul_f32 v[106:107], v[0:1], v[0:1]
	v_mov_b32_e32 v76, v104
	v_mov_b32_e32 v88, v105
	v_mov_b32_e32 v72, v107
	v_mov_b32_e32 v107, v3
	v_pk_add_f32 v[76:77], v[76:77], v[88:89]
	v_pk_add_f32 v[2:3], v[72:73], v[106:107]
	s_nop 0
	v_pk_add_f32 v[2:3], v[76:77], v[2:3]
	s_nop 0
	v_add_f32_e32 v2, v2, v3
	ds_bpermute_b32 v3, v124, v2
	s_waitcnt lgkmcnt(0)
	v_add_f32_e32 v2, v2, v3
	ds_bpermute_b32 v3, v125, v2
	s_waitcnt lgkmcnt(0)
	v_add_f32_e32 v2, v2, v3
	ds_bpermute_b32 v3, v126, v2
	s_waitcnt lgkmcnt(0)
	v_add_f32_e32 v2, v2, v3
	ds_bpermute_b32 v3, v127, v2
	s_waitcnt lgkmcnt(0)
	v_add_f32_e32 v2, v2, v3
	ds_bpermute_b32 v3, v130, v2
	s_waitcnt lgkmcnt(0)
	v_add_f32_e32 v2, v2, v3
	ds_bpermute_b32 v3, v131, v2
	s_waitcnt lgkmcnt(0)
	v_add_f32_e32 v2, v2, v3
	v_fmamk_f32 v2, v2, 0x3a000000, v132
	v_mul_f32_e32 v3, 0x4b800000, v2
	v_cmp_gt_f32_e32 vcc, s24, v2
	s_nop 1
	v_cndmask_b32_e32 v2, v2, v3, vcc
	v_rsq_f32_e32 v72, v2
	v_lshl_add_u64 v[2:3], s[16:17], 0, v[66:67]
	v_mul_f32_e32 v73, 0x45800000, v72
	v_cndmask_b32_e32 v72, v72, v73, vcc
	v_pk_mul_f32 v[68:69], v[68:69], v[72:73] op_sel_hi:[1,0]
	v_pk_mul_f32 v[28:29], v[28:29], v[72:73] op_sel_hi:[1,0]
	s_nop 0
	v_pk_mul_f32 v[68:69], v[200:201], v[68:69]
	v_pk_mul_f32 v[28:29], v[202:203], v[28:29]
	v_cvt_pk_bf16_f32 v68, v68, v69
	v_cvt_pk_bf16_f32 v69, v28, v29
	v_add_co_u32_e32 v28, vcc, s25, v2
	v_pk_mul_f32 v[0:1], v[0:1], v[72:73] op_sel_hi:[1,0]
	s_nop 0
	v_addc_co_u32_e32 v29, vcc, 0, v3, vcc
	global_store_dwordx2 v[28:29], v[68:69], off
	s_nop 0
	v_pk_mul_f32 v[2:3], v[24:25], v[72:73] op_sel_hi:[1,0]
	v_pk_mul_f32 v[24:25], v[26:27], v[72:73] op_sel_hi:[1,0]
	s_nop 0
	v_pk_mul_f32 v[2:3], v[204:205], v[2:3]
	v_pk_mul_f32 v[24:25], v[206:207], v[24:25]
	v_cvt_pk_bf16_f32 v2, v2, v3
	v_cvt_pk_bf16_f32 v3, v24, v25
	global_store_dwordx2 v[28:29], v[2:3], off offset:512
	s_nop 0
	v_pk_mul_f32 v[2:3], v[20:21], v[72:73] op_sel_hi:[1,0]
	v_pk_mul_f32 v[20:21], v[22:23], v[72:73] op_sel_hi:[1,0]
	s_nop 0
	v_pk_mul_f32 v[2:3], v[208:209], v[2:3]
	v_pk_mul_f32 v[20:21], v[210:211], v[20:21]
	v_cvt_pk_bf16_f32 v2, v2, v3
	v_cvt_pk_bf16_f32 v3, v20, v21
	global_store_dwordx2 v[28:29], v[2:3], off offset:1024
	s_nop 0
	v_pk_mul_f32 v[2:3], v[16:17], v[72:73] op_sel_hi:[1,0]
	v_pk_mul_f32 v[16:17], v[18:19], v[72:73] op_sel_hi:[1,0]
	s_nop 0
	v_pk_mul_f32 v[2:3], v[212:213], v[2:3]
	v_pk_mul_f32 v[16:17], v[214:215], v[16:17]
	v_cvt_pk_bf16_f32 v2, v2, v3
	v_cvt_pk_bf16_f32 v3, v16, v17
	global_store_dwordx2 v[28:29], v[2:3], off offset:1536
	s_nop 0
	v_pk_mul_f32 v[2:3], v[12:13], v[72:73] op_sel_hi:[1,0]
	v_pk_mul_f32 v[12:13], v[14:15], v[72:73] op_sel_hi:[1,0]
	s_nop 0
	v_pk_mul_f32 v[2:3], v[2:3], v[216:217]
	v_pk_mul_f32 v[12:13], v[12:13], v[218:219]
	v_cvt_pk_bf16_f32 v2, v2, v3
	v_cvt_pk_bf16_f32 v3, v12, v13
	global_store_dwordx2 v[28:29], v[2:3], off offset:2048
	s_nop 0
	v_pk_mul_f32 v[2:3], v[8:9], v[72:73] op_sel_hi:[1,0]
	v_pk_mul_f32 v[8:9], v[10:11], v[72:73] op_sel_hi:[1,0]
	s_nop 0
	v_pk_mul_f32 v[2:3], v[2:3], v[220:221]
	v_pk_mul_f32 v[8:9], v[8:9], v[222:223]
	v_cvt_pk_bf16_f32 v2, v2, v3
	v_cvt_pk_bf16_f32 v3, v8, v9
	global_store_dwordx2 v[28:29], v[2:3], off offset:2560
	s_nop 0
	v_pk_mul_f32 v[2:3], v[4:5], v[72:73] op_sel_hi:[1,0]
	v_pk_mul_f32 v[4:5], v[6:7], v[72:73] op_sel_hi:[1,0]
	v_pk_mul_f32 v[6:7], v[30:31], v[72:73] op_sel_hi:[1,0]
	s_nop 0
	v_pk_mul_f32 v[2:3], v[2:3], v[224:225]
	v_pk_mul_f32 v[4:5], v[4:5], v[226:227]
	v_cvt_pk_bf16_f32 v2, v2, v3
	v_cvt_pk_bf16_f32 v3, v4, v5
	global_store_dwordx2 v[28:29], v[2:3], off offset:3072
	s_nop 0
	s_nop 0
	v_pk_mul_f32 v[2:3], v[6:7], v[228:229]
	v_pk_mul_f32 v[0:1], v[0:1], v[230:231]
	v_cvt_pk_bf16_f32 v2, v2, v3
	v_cvt_pk_bf16_f32 v3, v0, v1
	global_store_dwordx2 v[28:29], v[2:3], off offset:3584
	s_branch .LBB0_258

; __device__ __forceinline__ float bf_lo(unsigned u) { return __uint_as_float(u << 16); }
; __device__ __forceinline__ float bf_hi(unsigned u) { return __uint_as_float(u & 0xffff0000u); }
; template <bool XIN_BF, bool XOUT_BF>
; __device__ __forceinline__ void norm_load_x(const float* xp, const float* xs, const bf16_t* xb, int m, int lane, f32x4 (&v)[8]) {
;     if (XIN_BF) { const u32x2* xr = (const u32x2*)(xb + (size_t)m * D) + lane;
; #pragma unroll
;         for (int j = 0; j < 8; ++j) { const u32x2 w = __builtin_nontemporal_load(&xr[64 * j]); v[j] = (f32x4){bf_lo(w.x), bf_hi(w.x), bf_lo(w.y), bf_hi(w.y)}; }
;     } else { const float* xrow = (m < MP) ? xp + (size_t)m * D : xs + (size_t)(m - MP) * D; const f32x4* xr = (const f32x4*)xrow + lane;
; #pragma unroll
;         for (int j = 0; j < 8; ++j) v[j] = __builtin_nontemporal_load(&xr[64 * j]); }
; }
; template <bool XIN_BF, bool XOUT_BF>
; __device__ __forceinline__ void norm_pass(const float* xp, const float* xs, const bf16_t* xbin, const bf16_t* Y, const float* post, float scale, const float* pre, float* X, bf16_t* xbout, bf16_t* XN, int gw, int NGW, int lane, const float* PART = nullptr) {
;     f32x4 v[8]; u32x2 y[8];
;     norm_load_x<XIN_BF, XOUT_BF>(xp, xs, xbin, gw, lane, v); norm_load_y(Y, PART, gw, lane, y);
;     for (int m = gw; m < M; m += NGW) {
;         f32x4 vn[8]; u32x2 yn[8];
;         const int mn = m + NGW < M ? m + NGW : m;
;         norm_load_x<XIN_BF, XOUT_BF>(xp, xs, xbin, mn, lane, vn); norm_load_y(Y, PART, mn, lane, yn);
.LBB0_896:
	s_cmp_lt_i32 s88, 10
	s_cselect_b64 s[0:1], -1, 0
	s_and_b64 s[0:1], s[0:1], s[2:3]
	s_andn2_b64 vcc, exec, s[0:1]
	s_cbranch_vccnz .LBB0_902
	s_cmp_gt_i32 s74, 0x87ff
	s_cbranch_scc1 .LBB0_902
	s_ashr_i32 s75, s74, 31
	s_lshl_b64 s[10:11], s[74:75], 12
	s_add_u32 s4, s94, s10
	s_addc_u32 s5, s95, s11
	s_add_u32 s2, s84, s10
	s_waitcnt vmcnt(0)
	v_lshlrev_b32_e32 v0, 3, v128
	s_addc_u32 s3, s85, s11
	global_load_dwordx2 v[6:7], v0, s[2:3] nt
	global_load_dwordx2 v[8:9], v0, s[2:3] offset:512 nt
	global_load_dwordx2 v[10:11], v0, s[2:3] offset:1024 nt
	global_load_dwordx2 v[12:13], v0, s[2:3] offset:1536 nt
	global_load_dwordx2 v[14:15], v0, s[2:3] offset:2048 nt
	global_load_dwordx2 v[16:17], v0, s[2:3] offset:2560 nt
	global_load_dwordx2 v[18:19], v0, s[2:3] offset:3072 nt
	global_load_dwordx2 v[20:21], v0, s[2:3] offset:3584 nt
	s_load_dwordx2 s[6:7], s[42:43], 0x70
	s_load_dwordx2 s[12:13], s[42:43], 0xa0
	global_load_dwordx2 v[40:41], v0, s[4:5] offset:3584 nt
	global_load_dwordx2 v[38:39], v0, s[4:5] offset:3072 nt
	global_load_dwordx2 v[36:37], v0, s[4:5] offset:2560 nt
	global_load_dwordx2 v[34:35], v0, s[4:5] offset:2048 nt
	global_load_dwordx2 v[32:33], v0, s[4:5] offset:1536 nt
	global_load_dwordx2 v[30:31], v0, s[4:5] offset:1024 nt
	global_load_dwordx2 v[28:29], v0, s[4:5] offset:512 nt
	global_load_dwordx2 v[26:27], v0, s[4:5] nt
	v_mbcnt_lo_u32_b32 v22, -1, 0
	v_mbcnt_hi_u32_b32 v22, -1, v22
	v_and_b32_e32 v23, 64, v22
	v_xor_b32_e32 v24, 1, v22
	v_add_u32_e32 v23, 64, v23
	v_xor_b32_e32 v25, 2, v22
	v_cmp_lt_i32_e32 vcc, v24, v23
	v_xor_b32_e32 v42, 4, v22
	v_mov_b32_e32 v1, 0
	v_cndmask_b32_e32 v24, v22, v24, vcc
	v_cmp_lt_i32_e32 vcc, v25, v23
	v_xor_b32_e32 v43, 8, v22
	v_xor_b32_e32 v44, 16, v22
	v_cndmask_b32_e32 v25, v22, v25, vcc
	v_cmp_lt_i32_e32 vcc, v42, v23
	s_waitcnt lgkmcnt(0)
	s_cmp_lg_u64 s[12:13], 0
	v_xor_b32_e32 v45, 32, v22
	v_cndmask_b32_e32 v42, v22, v42, vcc
	v_cmp_lt_i32_e32 vcc, v43, v23
	s_cselect_b64 s[4:5], -1, 0
	s_ashr_i32 s73, s72, 31
	v_cndmask_b32_e32 v43, v22, v43, vcc
	v_cmp_lt_i32_e32 vcc, v44, v23
	s_mov_b64 s[14:15], 0x1800
	s_mov_b64 s[16:17], 0x1c00
	v_cndmask_b32_e32 v44, v22, v44, vcc
	v_cmp_lt_i32_e32 vcc, v45, v23
	v_lshl_add_u64 v[2:3], s[84:85], 0, v[0:1]
	v_lshl_add_u64 v[4:5], s[94:95], 0, v[0:1]
	v_cndmask_b32_e32 v22, v22, v45, vcc
	v_lshlrev_b32_e32 v92, 2, v24
	v_lshlrev_b32_e32 v93, 2, v25
	v_lshlrev_b32_e32 v94, 2, v42
	v_lshlrev_b32_e32 v95, 2, v43
	v_lshlrev_b32_e32 v96, 2, v44
	v_lshlrev_b32_e32 v97, 2, v22
	v_mov_b32_e32 v98, 0x358637bd
	s_waitcnt vmcnt(15)
	v_lshlrev_b32_e32 v70, 16, v6
	s_waitcnt vmcnt(14)
	v_lshlrev_b32_e32 v66, 16, v8
	v_and_b32_e32 v67, 0xffff0000, v8
	v_lshlrev_b32_e32 v68, 16, v9
	v_and_b32_e32 v69, 0xffff0000, v9
	v_lshlrev_b32_e32 v8, 4, v128
	v_mov_b32_e32 v9, v1
	v_and_b32_e32 v71, 0xffff0000, v6
	v_lshlrev_b32_e32 v72, 16, v7
	v_and_b32_e32 v73, 0xffff0000, v7
	v_lshl_add_u64 v[6:7], s[6:7], 0, v[8:9]
	v_lshl_add_u64 v[8:9], s[12:13], 0, v[8:9]
	s_mov_b64 s[6:7], 0x1000
	s_waitcnt vmcnt(13)
	v_lshlrev_b32_e32 v62, 16, v10
	v_and_b32_e32 v63, 0xffff0000, v10
	v_lshlrev_b32_e32 v64, 16, v11
	v_and_b32_e32 v65, 0xffff0000, v11
	s_waitcnt vmcnt(9)
	v_lshlrev_b32_e32 v46, 16, v18
	v_and_b32_e32 v47, 0xffff0000, v18
	v_lshlrev_b32_e32 v48, 16, v19
	v_and_b32_e32 v49, 0xffff0000, v19
	v_lshl_add_u64 v[10:11], v[6:7], 0, s[6:7]
	v_lshl_add_u64 v[18:19], v[8:9], 0, s[6:7]
	s_lshl_b64 s[6:7], s[72:73], 12
	s_mov_b64 s[12:13], 0x1400
	s_add_u32 s10, s86, s10
	v_lshlrev_b32_e32 v58, 16, v12
	v_and_b32_e32 v59, 0xffff0000, v12
	v_lshlrev_b32_e32 v60, 16, v13
	v_and_b32_e32 v61, 0xffff0000, v13
	v_lshlrev_b32_e32 v54, 16, v14
	v_and_b32_e32 v55, 0xffff0000, v14
	v_lshlrev_b32_e32 v56, 16, v15
	v_and_b32_e32 v57, 0xffff0000, v15
	v_lshlrev_b32_e32 v50, 16, v16
	v_and_b32_e32 v51, 0xffff0000, v16
	v_lshlrev_b32_e32 v52, 16, v17
	v_and_b32_e32 v53, 0xffff0000, v17
	s_waitcnt vmcnt(8)
	v_lshlrev_b32_e32 v42, 16, v20
	v_and_b32_e32 v43, 0xffff0000, v20
	v_lshlrev_b32_e32 v44, 16, v21
	v_and_b32_e32 v45, 0xffff0000, v21
	v_lshl_add_u64 v[12:13], v[6:7], 0, s[12:13]
	v_lshl_add_u64 v[14:15], v[6:7], 0, s[14:15]
	v_lshl_add_u64 v[16:17], v[6:7], 0, s[16:17]
	v_lshl_add_u64 v[20:21], v[8:9], 0, s[12:13]
	v_lshl_add_u64 v[22:23], v[8:9], 0, s[14:15]
	v_lshl_add_u64 v[24:25], v[8:9], 0, s[16:17]
	s_addc_u32 s11, s87, s11
	s_mov_b32 s14, 0x800000
	s_mov_b32 s15, 0xad00000
	s_mov_b32 s16, s74
	global_load_dwordx4 v[140:143], v[6:7], off
	global_load_dwordx4 v[144:147], v[6:7], off offset:1024
	global_load_dwordx4 v[148:151], v[6:7], off offset:2048
	global_load_dwordx4 v[152:155], v[6:7], off offset:3072
	global_load_dwordx4 v[156:159], v[10:11], off
	global_load_dwordx4 v[160:163], v[12:13], off
	global_load_dwordx4 v[164:167], v[14:15], off
	global_load_dwordx4 v[168:171], v[16:17], off
	global_load_dwordx4 v[172:175], v[8:9], off
	global_load_dwordx4 v[176:179], v[8:9], off offset:1024
	global_load_dwordx4 v[180:183], v[8:9], off offset:2048
	global_load_dwordx4 v[184:187], v[8:9], off offset:3072
	global_load_dwordx4 v[188:191], v[18:19], off
	global_load_dwordx4 v[192:195], v[20:21], off
	global_load_dwordx4 v[196:199], v[22:23], off
	global_load_dwordx4 v[200:203], v[24:25], off
	s_waitcnt vmcnt(0)
	s_branch .LBB0_900
; __device__ __forceinline__ float bf_lo(unsigned u) { return __uint_as_float(u << 16); }
; __device__ __forceinline__ float bf_hi(unsigned u) { return __uint_as_float(u & 0xffff0000u); }
; template <bool XIN_BF, bool XOUT_BF>
; __device__ __forceinline__ void norm_pass(const float* xp, const float* xs, const bf16_t* xbin, const bf16_t* Y, const float* post, float scale, const float* pre, float* X, bf16_t* xbout, bf16_t* XN, int gw, int NGW, int lane, const float* PART = nullptr) {
;     ...
;     for (int m = gw; m < M; m += NGW) {
;         f32x4 vn[8]; u32x2 yn[8];
;         const int mn = m + NGW < M ? m + NGW : m;
;         norm_load_x<XIN_BF, XOUT_BF>(xp, xs, xbin, mn, lane, vn); norm_load_y(Y, PART, mn, lane, yn);
;         float s = 0.f;
; #pragma unroll
;         for (int j = 0; j < 8; ++j) { const float a = bf_lo(y[j].x), b = bf_hi(y[j].x), c = bf_lo(y[j].y), d = bf_hi(y[j].y); s += (a * a + b * b) + (c * c + d * d); }
;         const float rs = rsqrtf(wave_sum(s) * (1.f / D) + EPS) * scale; float s2 = 0.f;
.LBB0_899:
	s_add_u32 s2, s2, s6
	s_addc_u32 s3, s3, s7
	s_add_u32 s10, s10, s6
	s_waitcnt vmcnt(23)
	v_lshlrev_b32_e32 v70, 16, v88
	v_and_b32_e32 v71, 0xffff0000, v88
	v_lshlrev_b32_e32 v72, 16, v89
	v_and_b32_e32 v73, 0xffff0000, v89
	s_waitcnt vmcnt(22)
	v_lshlrev_b32_e32 v66, 16, v86
	v_and_b32_e32 v67, 0xffff0000, v86
	v_lshlrev_b32_e32 v68, 16, v87
	v_and_b32_e32 v69, 0xffff0000, v87
	s_waitcnt vmcnt(21)
	v_lshlrev_b32_e32 v62, 16, v84
	v_and_b32_e32 v63, 0xffff0000, v84
	v_lshlrev_b32_e32 v64, 16, v85
	v_and_b32_e32 v65, 0xffff0000, v85
	s_waitcnt vmcnt(20)
	v_lshlrev_b32_e32 v58, 16, v82
	v_and_b32_e32 v59, 0xffff0000, v82
	v_lshlrev_b32_e32 v60, 16, v83
	v_and_b32_e32 v61, 0xffff0000, v83
	s_waitcnt vmcnt(19)
	v_lshlrev_b32_e32 v54, 16, v80
	v_and_b32_e32 v55, 0xffff0000, v80
	v_lshlrev_b32_e32 v56, 16, v81
	v_and_b32_e32 v57, 0xffff0000, v81
	s_waitcnt vmcnt(18)
	v_lshlrev_b32_e32 v50, 16, v78
	v_and_b32_e32 v51, 0xffff0000, v78
	v_lshlrev_b32_e32 v52, 16, v79
	v_and_b32_e32 v53, 0xffff0000, v79
	s_waitcnt vmcnt(17)
	v_lshlrev_b32_e32 v46, 16, v76
	v_and_b32_e32 v47, 0xffff0000, v76
	v_lshlrev_b32_e32 v48, 16, v77
	v_and_b32_e32 v49, 0xffff0000, v77
	s_waitcnt vmcnt(16)
	v_lshlrev_b32_e32 v42, 16, v74
	v_and_b32_e32 v43, 0xffff0000, v74
	v_lshlrev_b32_e32 v44, 16, v75
	s_addc_u32 s11, s11, s7
	s_andn2_b64 vcc, exec, s[12:13]
	v_and_b32_e32 v45, 0xffff0000, v75
	s_cbranch_vccz .LBB0_902
.LBB0_900:
	s_nop 0
	s_nop 0
	s_waitcnt vmcnt(15)
	v_and_b32_e32 v105, 0xffff0000, v27
	s_waitcnt vmcnt(14)
	v_and_b32_e32 v107, 0xffff0000, v29
	v_lshlrev_b32_e32 v104, 16, v27
	v_and_b32_e32 v91, 0xffff0000, v26
	v_lshlrev_b32_e32 v106, 16, v29
	v_lshlrev_b32_e32 v108, 16, v28
	v_and_b32_e32 v109, 0xffff0000, v28
	v_mov_b32_e32 v28, v105
	v_mov_b32_e32 v29, v107
	v_lshlrev_b32_e32 v90, 16, v26
	v_mov_b32_e32 v26, v104
	v_mov_b32_e32 v27, v106
	v_pk_mul_f32 v[28:29], v[28:29], v[28:29]
	v_mov_b32_e32 v74, v91
	v_mov_b32_e32 v75, v109
	v_pk_fma_f32 v[26:27], v[26:27], v[26:27], v[28:29]
	v_mov_b32_e32 v28, v90
	v_mov_b32_e32 v29, v108
	v_pk_mul_f32 v[74:75], v[74:75], v[74:75]
	s_waitcnt vmcnt(13)
	v_and_b32_e32 v111, 0xffff0000, v31
	v_and_b32_e32 v113, 0xffff0000, v30
	v_pk_fma_f32 v[28:29], v[28:29], v[28:29], v[74:75]
	v_lshlrev_b32_e32 v110, 16, v31
	v_lshlrev_b32_e32 v112, 16, v30
	v_mov_b32_e32 v30, v113
	v_mov_b32_e32 v31, v111
	v_pk_add_f32 v[26:27], v[28:29], v[26:27]
	v_mov_b32_e32 v28, v112
	v_mov_b32_e32 v29, v110
	v_pk_mul_f32 v[30:31], v[30:31], v[30:31]
	s_waitcnt vmcnt(12)
	v_and_b32_e32 v115, 0xffff0000, v33
	v_and_b32_e32 v117, 0xffff0000, v32
	v_pk_fma_f32 v[28:29], v[28:29], v[28:29], v[30:31]
	v_lshlrev_b32_e32 v114, 16, v33
	v_mul_f32_e32 v30, v115, v115
	v_lshlrev_b32_e32 v116, 16, v32
	v_mul_f32_e32 v32, v117, v117
	s_waitcnt vmcnt(11)
	v_lshlrev_b32_e32 v118, 16, v35
	v_and_b32_e32 v119, 0xffff0000, v35
	v_lshlrev_b32_e32 v120, 16, v34
	v_and_b32_e32 v121, 0xffff0000, v34
	v_pk_add_f32 v[26:27], v[26:27], v[26:27] op_sel:[0,1] op_sel_hi:[1,0]
	v_pk_add_f32 v[28:29], v[28:29], v[28:29] op_sel:[0,1] op_sel_hi:[1,0]
	v_pk_fma_f32 v[30:31], v[114:115], v[114:115], v[30:31] op_sel_hi:[1,1,0]
	v_pk_fma_f32 v[32:33], v[116:117], v[116:117], v[32:33] op_sel_hi:[1,1,0]
	v_pk_mul_f32 v[74:75], v[118:119], v[118:119]
	v_pk_mul_f32 v[34:35], v[120:121], v[120:121]
	v_mov_b32_e32 v33, v74
	v_mov_b32_e32 v31, v75
	v_mov_b32_e32 v27, v34
	v_mov_b32_e32 v29, v35
	v_pk_add_f32 v[30:31], v[32:33], v[30:31]
	v_pk_add_f32 v[26:27], v[26:27], v[28:29]
	s_waitcnt vmcnt(10)
	v_and_b32_e32 v123, 0xffff0000, v37
	v_and_b32_e32 v125, 0xffff0000, v36
	v_pk_add_f32 v[26:27], v[26:27], v[30:31]
	v_lshlrev_b32_e32 v122, 16, v37
	v_lshlrev_b32_e32 v124, 16, v36
	v_mov_b32_e32 v30, v125
	v_mov_b32_e32 v31, v123
	v_mov_b32_e32 v28, v124
	v_mov_b32_e32 v29, v122
	v_pk_mul_f32 v[30:31], v[30:31], v[30:31]
	s_waitcnt vmcnt(9)
	v_and_b32_e32 v127, 0xffff0000, v39
	v_and_b32_e32 v131, 0xffff0000, v38
	v_pk_fma_f32 v[28:29], v[28:29], v[28:29], v[30:31]
	v_lshlrev_b32_e32 v126, 16, v39
	v_mul_f32_e32 v30, v127, v127
	v_lshlrev_b32_e32 v130, 16, v38
	v_mul_f32_e32 v32, v131, v131
	s_waitcnt vmcnt(8)
	v_lshlrev_b32_e32 v132, 16, v41
	v_and_b32_e32 v133, 0xffff0000, v41
	v_lshlrev_b32_e32 v134, 16, v40
	v_and_b32_e32 v135, 0xffff0000, v40
	v_pk_add_f32 v[26:27], v[26:27], v[26:27] op_sel:[0,1] op_sel_hi:[1,0]
	v_pk_add_f32 v[28:29], v[28:29], v[28:29] op_sel:[0,1] op_sel_hi:[1,0]
	v_pk_fma_f32 v[30:31], v[126:127], v[126:127], v[30:31] op_sel_hi:[1,1,0]
	v_pk_fma_f32 v[32:33], v[130:131], v[130:131], v[32:33] op_sel_hi:[1,1,0]
	v_pk_mul_f32 v[34:35], v[132:133], v[132:133]
	v_pk_mul_f32 v[36:37], v[134:135], v[134:135]
	v_mov_b32_e32 v33, v34
	v_mov_b32_e32 v31, v35
	v_mov_b32_e32 v27, v36
	v_mov_b32_e32 v29, v37
	v_pk_add_f32 v[30:31], v[32:33], v[30:31]
	v_pk_add_f32 v[26:27], v[26:27], v[28:29]
	s_mov_b32 s17, s16
	v_pk_add_f32 v[26:27], v[26:27], v[30:31]
	s_add_i32 s16, s16, s72
	v_add_f32_e32 v26, v26, v27
	ds_bpermute_b32 v27, v92, v26
	s_cmp_gt_i32 s16, 0x87ff
	s_cselect_b64 s[12:13], -1, 0
	s_cmp_lt_i32 s16, 0x8800
	s_cselect_b32 s18, s16, s17
	s_waitcnt lgkmcnt(0)
	v_add_f32_e32 v26, v26, v27
	ds_bpermute_b32 v27, v93, v26
	s_ashr_i32 s19, s18, 31
	s_lshl_b64 s[18:19], s[18:19], 12
	v_lshl_add_u64 v[40:41], v[4:5], 0, s[18:19]
	v_lshl_add_u64 v[136:137], s[2:3], 0, v[0:1]
	s_waitcnt lgkmcnt(0)
; __device__ __forceinline__ unsigned cvt_pk_bf16(float lo, float hi) { const f32x2_cv v = {lo, hi}; return __builtin_bit_cast(unsigned, __builtin_convertvector(v, bf16x2_cv)); }
; __device__ __forceinline__ float bf_lo(unsigned u) { return __uint_as_float(u << 16); }
; __device__ __forceinline__ float bf_hi(unsigned u) { return __uint_as_float(u & 0xffff0000u); }
; template <bool XIN_BF, bool XOUT_BF>
; __device__ __forceinline__ void norm_pass(const float* xp, const float* xs, const bf16_t* xbin, const bf16_t* Y, const float* post, float scale, const float* pre, float* X, bf16_t* xbout, bf16_t* XN, int gw, int NGW, int lane, const float* PART = nullptr) {
;     ...
;         const int mn = m + NGW < M ? m + NGW : m;
;         norm_load_x<XIN_BF, XOUT_BF>(xp, xs, xbin, mn, lane, vn); norm_load_y(Y, PART, mn, lane, yn);
;         float s = 0.f;
; #pragma unroll
;         for (int j = 0; j < 8; ++j) { const float a = bf_lo(y[j].x), b = bf_hi(y[j].x), c = bf_lo(y[j].y), d = bf_hi(y[j].y); s += (a * a + b * b) + (c * c + d * d); }
;         const float rs = rsqrtf(wave_sum(s) * (1.f / D) + EPS) * scale; float s2 = 0.f;
; #pragma unroll
;         for (int j = 0; j < 8; ++j) { const f32x4 g = ((const f32x4*)post + lane)[64 * j];
;             v[j].x += bf_lo(y[j].x) * rs * g.x; v[j].y += bf_hi(y[j].x) * rs * g.y; v[j].z += bf_lo(y[j].y) * rs * g.z; v[j].w += bf_hi(y[j].y) * rs * g.w;
;             s2 += (v[j].x * v[j].x + v[j].y * v[j].y) + (v[j].z * v[j].z + v[j].w * v[j].w);
;             if (XOUT_BF) { u32x2 w; w.x = cvt_pk_bf16(v[j].x, v[j].y); w.y = cvt_pk_bf16(v[j].z, v[j].w); __builtin_nontemporal_store(w, &((u32x2*)(xbout + (size_t)m * D) + lane)[64 * j]); }
;             else __builtin_nontemporal_store(v[j], &((f32x4*)(X + (size_t)m * D) + lane)[64 * j]); }
	v_add_f32_e32 v28, v26, v27
	ds_bpermute_b32 v29, v94, v28
	v_lshl_add_u64 v[26:27], v[2:3], 0, s[18:19]
	global_load_dwordx2 v[88:89], v[26:27], off nt
	global_load_dwordx2 v[86:87], v[26:27], off offset:512 nt
	global_load_dwordx2 v[84:85], v[26:27], off offset:1024 nt
	global_load_dwordx2 v[82:83], v[26:27], off offset:1536 nt
	global_load_dwordx2 v[80:81], v[26:27], off offset:2048 nt
	global_load_dwordx2 v[78:79], v[26:27], off offset:2560 nt
	global_load_dwordx2 v[76:77], v[26:27], off offset:3072 nt
	global_load_dwordx2 v[74:75], v[26:27], off offset:3584 nt
	s_waitcnt lgkmcnt(0)
	v_add_f32_e32 v28, v28, v29
	ds_bpermute_b32 v29, v95, v28
	s_waitcnt lgkmcnt(0)
	v_add_f32_e32 v28, v28, v29
	ds_bpermute_b32 v29, v96, v28
	s_waitcnt lgkmcnt(0)
	v_add_f32_e32 v34, v28, v29
	ds_bpermute_b32 v35, v97, v34
	global_load_dwordx2 v[26:27], v[40:41], off nt
	global_load_dwordx2 v[28:29], v[40:41], off offset:512 nt
	global_load_dwordx2 v[30:31], v[40:41], off offset:1024 nt
	global_load_dwordx2 v[32:33], v[40:41], off offset:1536 nt
	s_waitcnt lgkmcnt(0)
	v_add_f32_e32 v34, v34, v35
	v_fmamk_f32 v34, v34, 0x3a000000, v98
	v_mul_f32_e32 v35, 0x4b800000, v34
	v_cmp_gt_f32_e32 vcc, s14, v34
	s_nop 1
	v_cndmask_b32_e32 v34, v34, v35, vcc
	v_rsq_f32_e32 v99, v34
	global_load_dwordx2 v[34:35], v[40:41], off offset:2048 nt
	global_load_dwordx2 v[36:37], v[40:41], off offset:2560 nt
	global_load_dwordx2 v[38:39], v[40:41], off offset:3072 nt
	s_nop 0
	global_load_dwordx2 v[40:41], v[40:41], off offset:3584 nt
	v_mul_f32_e32 v138, 0x45800000, v99
	v_cndmask_b32_e32 v138, v99, v138, vcc
	v_pk_mul_f32 v[90:91], v[138:139], v[90:91] op_sel_hi:[0,1]
	s_nop 0
	v_pk_fma_f32 v[90:91], v[140:141], v[90:91], v[70:71]
	v_pk_mul_f32 v[70:71], v[138:139], v[104:105] op_sel_hi:[0,1]
	v_pk_fma_f32 v[70:71], v[142:143], v[70:71], v[72:73]
	v_cvt_pk_bf16_f32 v72, v90, v91
	v_cvt_pk_bf16_f32 v73, v70, v71
	global_store_dwordx2 v[136:137], v[72:73], off nt
	s_nop 0
	v_pk_mul_f32 v[72:73], v[138:139], v[108:109] op_sel_hi:[0,1]
	v_pk_mul_f32 v[104:105], v[138:139], v[106:107] op_sel_hi:[0,1]
	s_andn2_b64 vcc, exec, s[4:5]
	s_nop 0
	v_pk_fma_f32 v[66:67], v[144:145], v[72:73], v[66:67]
	v_pk_fma_f32 v[68:69], v[146:147], v[104:105], v[68:69]
	v_cvt_pk_bf16_f32 v72, v66, v67
	v_cvt_pk_bf16_f32 v73, v68, v69
	global_store_dwordx2 v[136:137], v[72:73], off offset:512 nt
	s_nop 0
	v_pk_mul_f32 v[72:73], v[138:139], v[112:113] op_sel_hi:[0,1]
	v_pk_mul_f32 v[104:105], v[138:139], v[110:111] op_sel_hi:[0,1]
	s_nop 0
	v_pk_fma_f32 v[62:63], v[148:149], v[72:73], v[62:63]
	v_pk_fma_f32 v[64:65], v[150:151], v[104:105], v[64:65]
	v_cvt_pk_bf16_f32 v72, v62, v63
	v_cvt_pk_bf16_f32 v73, v64, v65
	global_store_dwordx2 v[136:137], v[72:73], off offset:1024 nt
	s_nop 0
	v_pk_mul_f32 v[72:73], v[138:139], v[116:117] op_sel_hi:[0,1]
	v_pk_mul_f32 v[104:105], v[138:139], v[114:115] op_sel_hi:[0,1]
	s_nop 0
	v_pk_fma_f32 v[58:59], v[152:153], v[72:73], v[58:59]
	v_pk_fma_f32 v[60:61], v[154:155], v[104:105], v[60:61]
	v_cvt_pk_bf16_f32 v72, v58, v59
	v_cvt_pk_bf16_f32 v73, v60, v61
	global_store_dwordx2 v[136:137], v[72:73], off offset:1536 nt
	s_nop 0
	v_pk_mul_f32 v[72:73], v[138:139], v[120:121] op_sel_hi:[0,1]
	v_pk_mul_f32 v[104:105], v[138:139], v[118:119] op_sel_hi:[0,1]
	s_nop 0
	v_pk_fma_f32 v[54:55], v[156:157], v[72:73], v[54:55]
	v_pk_fma_f32 v[56:57], v[158:159], v[104:105], v[56:57]
	v_cvt_pk_bf16_f32 v72, v54, v55
	v_cvt_pk_bf16_f32 v73, v56, v57
	global_store_dwordx2 v[136:137], v[72:73], off offset:2048 nt
	s_nop 0
	v_pk_mul_f32 v[72:73], v[138:139], v[124:125] op_sel_hi:[0,1]
	v_pk_mul_f32 v[104:105], v[138:139], v[122:123] op_sel_hi:[0,1]
	s_nop 0
	v_pk_fma_f32 v[50:51], v[72:73], v[160:161], v[50:51]
	v_pk_fma_f32 v[52:53], v[104:105], v[162:163], v[52:53]
	v_cvt_pk_bf16_f32 v72, v50, v51
	v_cvt_pk_bf16_f32 v73, v52, v53
	global_store_dwordx2 v[136:137], v[72:73], off offset:2560 nt
	s_nop 0
	v_pk_mul_f32 v[72:73], v[138:139], v[130:131] op_sel_hi:[0,1]
	v_pk_mul_f32 v[104:105], v[138:139], v[126:127] op_sel_hi:[0,1]
	s_nop 0
	v_pk_fma_f32 v[46:47], v[72:73], v[164:165], v[46:47]
	v_pk_fma_f32 v[48:49], v[104:105], v[166:167], v[48:49]
	v_cvt_pk_bf16_f32 v72, v46, v47
	v_cvt_pk_bf16_f32 v73, v48, v49
	global_store_dwordx2 v[136:137], v[72:73], off offset:3072 nt
	s_nop 0
	v_pk_mul_f32 v[72:73], v[138:139], v[134:135] op_sel_hi:[0,1]
	v_pk_mul_f32 v[104:105], v[138:139], v[132:133] op_sel_hi:[0,1]
	s_nop 0
	v_pk_fma_f32 v[72:73], v[72:73], v[168:169], v[42:43]
	v_pk_fma_f32 v[42:43], v[104:105], v[170:171], v[44:45]
	v_cvt_pk_bf16_f32 v44, v72, v73
	v_cvt_pk_bf16_f32 v45, v42, v43
	global_store_dwordx2 v[136:137], v[44:45], off offset:3584 nt
	s_cbranch_vccnz .LBB0_899
; __device__ __forceinline__ unsigned cvt_pk_bf16(float lo, float hi) { const f32x2_cv v = {lo, hi}; return __builtin_bit_cast(unsigned, __builtin_convertvector(v, bf16x2_cv)); }
; template <bool XIN_BF, bool XOUT_BF>
; __device__ __forceinline__ void norm_pass(const float* xp, const float* xs, const bf16_t* xbin, const bf16_t* Y, const float* post, float scale, const float* pre, float* X, bf16_t* xbout, bf16_t* XN, int gw, int NGW, int lane, const float* PART = nullptr) {
;     ...
;             s2 += (v[j].x * v[j].x + v[j].y * v[j].y) + (v[j].z * v[j].z + v[j].w * v[j].w);
;             if (XOUT_BF) { u32x2 w; w.x = cvt_pk_bf16(v[j].x, v[j].y); w.y = cvt_pk_bf16(v[j].z, v[j].w); __builtin_nontemporal_store(w, &((u32x2*)(xbout + (size_t)m * D) + lane)[64 * j]); }
;             else __builtin_nontemporal_store(v[j], &((f32x4*)(X + (size_t)m * D) + lane)[64 * j]); }
;         if (pre) {
;             const float r2 = rsqrtf(wave_sum(s2) * (1.f / D) + EPS); u32x2* o8 = (u32x2*)(XN + (size_t)m * D) + lane;
; #pragma unroll
;             for (int j = 0; j < 8; ++j) { const f32x4 g = ((const f32x4*)pre + lane)[64 * j]; u32x2 w; w.x = cvt_pk_bf16(v[j].x * r2 * g.x, v[j].y * r2 * g.y); w.y = cvt_pk_bf16(v[j].z * r2 * g.z, v[j].w * r2 * g.w); o8[64 * j] = w; }
;         }
	v_mov_b32_e32 v100, v91
	v_mov_b32_e32 v101, v67
	v_mov_b32_e32 v44, v90
	v_mov_b32_e32 v45, v66
	v_pk_mul_f32 v[100:101], v[100:101], v[100:101]
	v_mov_b32_e32 v102, v70
	v_mov_b32_e32 v103, v68
	v_pk_fma_f32 v[44:45], v[44:45], v[44:45], v[100:101]
	v_mov_b32_e32 v100, v71
	v_mov_b32_e32 v101, v69
	v_pk_mul_f32 v[102:103], v[102:103], v[102:103]
	v_pk_mul_f32 v[110:111], v[54:55], v[54:55]
	v_pk_fma_f32 v[100:101], v[100:101], v[100:101], v[102:103]
	v_pk_mov_b32 v[102:103], v[62:63], v[64:65] op_sel:[1,0]
	v_pk_add_f32 v[44:45], v[44:45], v[100:101]
	v_mov_b32_e32 v100, v62
	v_mov_b32_e32 v101, v65
	v_pk_mul_f32 v[102:103], v[102:103], v[102:103]
	v_pk_add_f32 v[44:45], v[44:45], v[44:45] op_sel_hi:[0,1]
	v_pk_fma_f32 v[100:101], v[100:101], v[100:101], v[102:103]
	v_mul_f32_e32 v44, v58, v58
	v_pk_add_f32 v[104:105], v[100:101], v[100:101] op_sel_hi:[0,1]
	s_nop 0
	v_pk_fma_f32 v[106:107], v[58:59], v[58:59], v[44:45] op_sel_hi:[1,1,0]
	v_mul_f32_e32 v44, v60, v60
	v_pk_fma_f32 v[108:109], v[60:61], v[60:61], v[44:45] op_sel_hi:[1,1,0]
	v_pk_mul_f32 v[112:113], v[56:57], v[56:57]
	v_mov_b32_e32 v106, v110
	v_mov_b32_e32 v108, v111
	v_mov_b32_e32 v104, v113
	v_mov_b32_e32 v113, v45
	v_pk_add_f32 v[106:107], v[106:107], v[108:109]
	v_pk_add_f32 v[44:45], v[104:105], v[112:113]
	v_mov_b32_e32 v104, v50
	v_pk_add_f32 v[44:45], v[106:107], v[44:45]
	v_pk_mov_b32 v[106:107], v[50:51], v[52:53] op_sel:[1,0]
	v_mov_b32_e32 v105, v53
	v_pk_mul_f32 v[106:107], v[106:107], v[106:107]
	v_mul_f32_e32 v108, v49, v49
	v_pk_fma_f32 v[104:105], v[104:105], v[104:105], v[106:107]
	v_mul_f32_e32 v106, v47, v47
	v_pk_add_f32 v[44:45], v[44:45], v[44:45] op_sel:[0,1] op_sel_hi:[1,0]
	v_pk_add_f32 v[104:105], v[104:105], v[104:105] op_sel:[0,1] op_sel_hi:[1,0]
	v_pk_fma_f32 v[106:107], v[46:47], v[46:47], v[106:107] op_sel_hi:[1,1,0]
	v_pk_fma_f32 v[108:109], v[48:49], v[48:49], v[108:109] op_sel_hi:[1,1,0]
	v_pk_mul_f32 v[110:111], v[72:73], v[72:73]
	v_pk_mul_f32 v[112:113], v[42:43], v[42:43]
	v_mov_b32_e32 v107, v110
	v_mov_b32_e32 v109, v111
	v_mov_b32_e32 v105, v113
	v_mov_b32_e32 v45, v112
	v_pk_add_f32 v[106:107], v[106:107], v[108:109]
	v_pk_add_f32 v[44:45], v[104:105], v[44:45]
	s_nop 0
	v_pk_add_f32 v[44:45], v[106:107], v[44:45]
	s_nop 0
	v_add_f32_e32 v44, v44, v45
	ds_bpermute_b32 v45, v92, v44
	s_waitcnt lgkmcnt(0)
	v_add_f32_e32 v44, v44, v45
	ds_bpermute_b32 v45, v93, v44
	s_waitcnt lgkmcnt(0)
	v_add_f32_e32 v44, v44, v45
	ds_bpermute_b32 v45, v94, v44
	s_waitcnt lgkmcnt(0)
	v_add_f32_e32 v44, v44, v45
	ds_bpermute_b32 v45, v95, v44
	s_waitcnt lgkmcnt(0)
	v_add_f32_e32 v44, v44, v45
	ds_bpermute_b32 v45, v96, v44
	s_waitcnt lgkmcnt(0)
	v_add_f32_e32 v44, v44, v45
	ds_bpermute_b32 v45, v97, v44
	s_waitcnt lgkmcnt(0)
	v_add_f32_e32 v44, v44, v45
	v_fmamk_f32 v44, v44, 0x3a000000, v98
	v_mul_f32_e32 v45, 0x4b800000, v44
	v_cmp_gt_f32_e32 vcc, s14, v44
	s_nop 1
	v_cndmask_b32_e32 v44, v44, v45, vcc
	v_rsq_f32_e32 v99, v44
	v_lshl_add_u64 v[44:45], s[10:11], 0, v[0:1]
	v_mul_f32_e32 v104, 0x45800000, v99
	v_cndmask_b32_e32 v104, v99, v104, vcc
	v_pk_mul_f32 v[90:91], v[90:91], v[104:105] op_sel_hi:[1,0]
	v_pk_mul_f32 v[70:71], v[70:71], v[104:105] op_sel_hi:[1,0]
	s_nop 0
	v_pk_mul_f32 v[90:91], v[172:173], v[90:91]
	v_pk_mul_f32 v[70:71], v[174:175], v[70:71]
	v_cvt_pk_bf16_f32 v90, v90, v91
	v_cvt_pk_bf16_f32 v91, v70, v71
	v_add_co_u32_e32 v70, vcc, s15, v44
	v_pk_mul_f32 v[42:43], v[42:43], v[104:105] op_sel_hi:[1,0]
	s_nop 0
	v_addc_co_u32_e32 v71, vcc, 0, v45, vcc
	global_store_dwordx2 v[70:71], v[90:91], off
	s_nop 0
	v_pk_mul_f32 v[44:45], v[66:67], v[104:105] op_sel_hi:[1,0]
	v_pk_mul_f32 v[66:67], v[68:69], v[104:105] op_sel_hi:[1,0]
	s_nop 0
	v_pk_mul_f32 v[44:45], v[176:177], v[44:45]
	v_pk_mul_f32 v[66:67], v[178:179], v[66:67]
	v_cvt_pk_bf16_f32 v44, v44, v45
	v_cvt_pk_bf16_f32 v45, v66, v67
	global_store_dwordx2 v[70:71], v[44:45], off offset:512
	s_nop 0
	v_pk_mul_f32 v[44:45], v[62:63], v[104:105] op_sel_hi:[1,0]
	v_pk_mul_f32 v[62:63], v[64:65], v[104:105] op_sel_hi:[1,0]
	s_nop 0
	v_pk_mul_f32 v[44:45], v[180:181], v[44:45]
	v_pk_mul_f32 v[62:63], v[182:183], v[62:63]
	v_cvt_pk_bf16_f32 v44, v44, v45
	v_cvt_pk_bf16_f32 v45, v62, v63
	global_store_dwordx2 v[70:71], v[44:45], off offset:1024
	s_nop 0
	v_pk_mul_f32 v[44:45], v[58:59], v[104:105] op_sel_hi:[1,0]
	v_pk_mul_f32 v[58:59], v[60:61], v[104:105] op_sel_hi:[1,0]
	s_nop 0
	v_pk_mul_f32 v[44:45], v[184:185], v[44:45]
	v_pk_mul_f32 v[58:59], v[186:187], v[58:59]
	v_cvt_pk_bf16_f32 v44, v44, v45
	v_cvt_pk_bf16_f32 v45, v58, v59
	global_store_dwordx2 v[70:71], v[44:45], off offset:1536
	s_nop 0
	v_pk_mul_f32 v[44:45], v[54:55], v[104:105] op_sel_hi:[1,0]
	v_pk_mul_f32 v[54:55], v[56:57], v[104:105] op_sel_hi:[1,0]
	s_nop 0
	v_pk_mul_f32 v[44:45], v[44:45], v[188:189]
	v_pk_mul_f32 v[54:55], v[54:55], v[190:191]
	v_cvt_pk_bf16_f32 v44, v44, v45
	v_cvt_pk_bf16_f32 v45, v54, v55
	global_store_dwordx2 v[70:71], v[44:45], off offset:2048
	s_nop 0
	v_pk_mul_f32 v[44:45], v[50:51], v[104:105] op_sel_hi:[1,0]
	v_pk_mul_f32 v[50:51], v[52:53], v[104:105] op_sel_hi:[1,0]
	s_nop 0
	v_pk_mul_f32 v[44:45], v[44:45], v[192:193]
	v_pk_mul_f32 v[50:51], v[50:51], v[194:195]
	v_cvt_pk_bf16_f32 v44, v44, v45
	v_cvt_pk_bf16_f32 v45, v50, v51
	global_store_dwordx2 v[70:71], v[44:45], off offset:2560
	s_nop 0
	v_pk_mul_f32 v[44:45], v[46:47], v[104:105] op_sel_hi:[1,0]
	v_pk_mul_f32 v[46:47], v[48:49], v[104:105] op_sel_hi:[1,0]
	v_pk_mul_f32 v[48:49], v[72:73], v[104:105] op_sel_hi:[1,0]
	s_nop 0
	v_pk_mul_f32 v[44:45], v[44:45], v[196:197]
	v_pk_mul_f32 v[46:47], v[46:47], v[198:199]
	v_cvt_pk_bf16_f32 v44, v44, v45
	v_cvt_pk_bf16_f32 v45, v46, v47
	global_store_dwordx2 v[70:71], v[44:45], off offset:3072
	s_nop 0
	s_nop 0
	v_pk_mul_f32 v[44:45], v[48:49], v[200:201]
	v_pk_mul_f32 v[42:43], v[42:43], v[202:203]
	v_cvt_pk_bf16_f32 v44, v44, v45
	v_cvt_pk_bf16_f32 v45, v42, v43
	global_store_dwordx2 v[70:71], v[44:45], off offset:3584
	s_branch .LBB0_899

; __device__ __forceinline__ float bf_lo(unsigned u) { return __uint_as_float(u << 16); }
; __device__ __forceinline__ float bf_hi(unsigned u) { return __uint_as_float(u & 0xffff0000u); }
; template <bool XIN_BF, bool XOUT_BF>
; __device__ __forceinline__ void norm_load_x(const float* xp, const float* xs, const bf16_t* xb, int m, int lane, f32x4 (&v)[8]) {
;     if (XIN_BF) { const u32x2* xr = (const u32x2*)(xb + (size_t)m * D) + lane;
; #pragma unroll
;         for (int j = 0; j < 8; ++j) { const u32x2 w = __builtin_nontemporal_load(&xr[64 * j]); v[j] = (f32x4){bf_lo(w.x), bf_hi(w.x), bf_lo(w.y), bf_hi(w.y)}; }
;     } else { const float* xrow = (m < MP) ? xp + (size_t)m * D : xs + (size_t)(m - MP) * D; const f32x4* xr = (const f32x4*)xrow + lane;
; #pragma unroll
;         for (int j = 0; j < 8; ++j) v[j] = __builtin_nontemporal_load(&xr[64 * j]); }
; }
; template <bool XIN_BF, bool XOUT_BF>
; __device__ __forceinline__ void norm_pass(const float* xp, const float* xs, const bf16_t* xbin, const bf16_t* Y, const float* post, float scale, const float* pre, float* X, bf16_t* xbout, bf16_t* XN, int gw, int NGW, int lane, const float* PART = nullptr) {
;     f32x4 v[8]; u32x2 y[8];
;     norm_load_x<XIN_BF, XOUT_BF>(xp, xs, xbin, gw, lane, v); norm_load_y(Y, PART, gw, lane, y);
;     for (int m = gw; m < M; m += NGW) {
;         f32x4 vn[8]; u32x2 yn[8];
;         const int mn = m + NGW < M ? m + NGW : m;
;         norm_load_x<XIN_BF, XOUT_BF>(xp, xs, xbin, mn, lane, vn); norm_load_y(Y, PART, mn, lane, yn);
.LBB0_1160:
	s_cmp_gt_i32 s74, 0x87ff
	s_cbranch_scc1 .LBB0_1196
	s_waitcnt vmcnt(10)
	v_lshlrev_b32_e32 v84, 16, v18
	v_and_b32_e32 v85, 0xffff0000, v18
	v_mbcnt_lo_u32_b32 v18, -1, 0
	v_mbcnt_hi_u32_b32 v18, -1, v18
	v_lshlrev_b32_e32 v86, 16, v19
	v_and_b32_e32 v87, 0xffff0000, v19
	v_and_b32_e32 v19, 64, v18
	v_lshlrev_b32_e32 v88, 16, v20
	v_and_b32_e32 v89, 0xffff0000, v20
	v_add_u32_e32 v19, 64, v19
	v_xor_b32_e32 v20, 1, v18
	v_cmp_lt_i32_e32 vcc, v20, v19
	s_load_dwordx2 s[4:5], s[42:43], 0xa8
	s_load_dwordx2 s[6:7], s[42:43], 0xc8
	v_cndmask_b32_e32 v20, v18, v20, vcc
	v_lshlrev_b32_e32 v110, 2, v20
	v_xor_b32_e32 v20, 2, v18
	v_cmp_lt_i32_e32 vcc, v20, v19
	v_mov_b32_e32 v1, 0
	v_lshlrev_b32_e32 v90, 16, v21
	v_cndmask_b32_e32 v20, v18, v20, vcc
	v_lshlrev_b32_e32 v111, 2, v20
	v_xor_b32_e32 v20, 4, v18
	v_cmp_lt_i32_e32 vcc, v20, v19
	v_and_b32_e32 v91, 0xffff0000, v21
	v_mov_b32_e32 v21, v1
	v_cndmask_b32_e32 v20, v18, v20, vcc
	v_lshlrev_b32_e32 v112, 2, v20
	v_xor_b32_e32 v20, 8, v18
	v_cmp_lt_i32_e32 vcc, v20, v19
	s_waitcnt lgkmcnt(0)
	s_cmp_lg_u64 s[6:7], 0
	v_lshlrev_b32_e32 v92, 16, v22
	v_cndmask_b32_e32 v20, v18, v20, vcc
	v_lshlrev_b32_e32 v113, 2, v20
	v_xor_b32_e32 v20, 16, v18
	v_cmp_lt_i32_e32 vcc, v20, v19
	v_and_b32_e32 v93, 0xffff0000, v22
	v_lshlrev_b32_e32 v94, 16, v23
	v_cndmask_b32_e32 v20, v18, v20, vcc
	v_lshlrev_b32_e32 v114, 2, v20
	v_xor_b32_e32 v20, 32, v18
	v_cmp_lt_i32_e32 vcc, v20, v19
	v_and_b32_e32 v95, 0xffff0000, v23
	v_lshlrev_b32_e32 v44, 2, v128
	v_cndmask_b32_e32 v18, v18, v20, vcc
	v_lshlrev_b32_e32 v20, 4, v128
	v_lshlrev_b32_e32 v115, 2, v18
	v_lshl_add_u64 v[18:19], s[4:5], 0, v[20:21]
	v_lshl_add_u64 v[20:21], s[6:7], 0, v[20:21]
	s_mov_b64 s[6:7], 0x1000
	s_cselect_b64 s[4:5], -1, 0
	v_lshl_add_u64 v[22:23], v[18:19], 0, s[6:7]
	v_lshl_add_u64 v[30:31], v[20:21], 0, s[6:7]
	s_add_u32 s6, s86, s10
	s_addc_u32 s7, s87, s11
	s_mov_b64 s[12:13], 0x1400
	s_mov_b64 s[14:15], 0x1800
	s_mov_b64 s[16:17], 0x1c00
	v_lshl_add_u64 v[42:43], s[6:7], 0, v[0:1]
	s_mov_b64 s[6:7], 0x13500e00
	s_ashr_i32 s73, s72, 31
	v_lshlrev_b32_e32 v104, 16, v28
	v_and_b32_e32 v105, 0xffff0000, v28
	v_lshlrev_b32_e32 v106, 16, v29
	v_and_b32_e32 v107, 0xffff0000, v29
	v_lshlrev_b32_e32 v100, 16, v26
	v_and_b32_e32 v101, 0xffff0000, v26
	v_lshlrev_b32_e32 v102, 16, v27
	v_and_b32_e32 v103, 0xffff0000, v27
	v_lshlrev_b32_e32 v96, 16, v24
	v_and_b32_e32 v97, 0xffff0000, v24
	v_lshlrev_b32_e32 v98, 16, v25
	v_and_b32_e32 v99, 0xffff0000, v25
	s_waitcnt vmcnt(9)
	v_lshlrev_b32_e32 v80, 16, v12
	v_and_b32_e32 v81, 0xffff0000, v12
	v_lshlrev_b32_e32 v82, 16, v13
	v_and_b32_e32 v83, 0xffff0000, v13
	s_waitcnt vmcnt(8)
	v_lshlrev_b32_e32 v76, 16, v10
	v_and_b32_e32 v77, 0xffff0000, v10
	v_lshlrev_b32_e32 v78, 16, v11
	v_and_b32_e32 v79, 0xffff0000, v11
	v_lshl_add_u64 v[10:11], s[84:85], 0, v[0:1]
	v_lshl_add_u64 v[12:13], s[94:95], 0, v[0:1]
	s_mov_b32 s3, 0
	v_lshl_add_u64 v[24:25], v[18:19], 0, s[12:13]
	v_lshl_add_u64 v[26:27], v[18:19], 0, s[14:15]
	v_lshl_add_u64 v[28:29], v[18:19], 0, s[16:17]
	v_lshl_add_u64 v[34:35], v[20:21], 0, s[12:13]
	v_lshl_add_u64 v[36:37], v[20:21], 0, s[14:15]
	v_lshl_add_u64 v[38:39], v[20:21], 0, s[16:17]
	v_lshl_add_u64 v[42:43], v[42:43], 0, s[6:7]
	s_lshl_b64 s[10:11], s[72:73], 12
	v_lshlrev_b32_e32 v0, 2, v44
	s_mov_b32 s16, 0x40000
	v_mov_b32_e32 v116, 0x358637bd
	s_mov_b32 s17, 0x800000
	s_mov_b32 s18, 0xf7800000
	s_mov_b32 s19, s74
	global_load_dwordx4 v[156:159], v[18:19], off
	global_load_dwordx4 v[160:163], v[18:19], off offset:1024
	global_load_dwordx4 v[164:167], v[18:19], off offset:2048
	global_load_dwordx4 v[168:171], v[18:19], off offset:3072
	global_load_dwordx4 v[172:175], v[22:23], off
	global_load_dwordx4 v[176:179], v[24:25], off
	global_load_dwordx4 v[180:183], v[26:27], off
	global_load_dwordx4 v[184:187], v[28:29], off
	global_load_dwordx4 v[188:191], v[20:21], off
	global_load_dwordx4 v[192:195], v[20:21], off offset:1024
	global_load_dwordx4 v[196:199], v[20:21], off offset:2048
	global_load_dwordx4 v[200:203], v[20:21], off offset:3072
	global_load_dwordx4 v[204:207], v[30:31], off
	global_load_dwordx4 v[208:211], v[34:35], off
	global_load_dwordx4 v[212:215], v[36:37], off
	global_load_dwordx4 v[216:219], v[38:39], off
	s_waitcnt vmcnt(0)
	s_branch .LBB0_1163
; __device__ __forceinline__ unsigned cvt_pk_bf16(float lo, float hi) { const f32x2_cv v = {lo, hi}; return __builtin_bit_cast(unsigned, __builtin_convertvector(v, bf16x2_cv)); }
; __device__ __forceinline__ void norm_load_y(const bf16_t* Y, const float* PART, int m, int lane, u32x2 (&y)[8]) {
;     ...
;     const int pm = m >> 8, q = pm - 16;
;     if (PART && q >= 0 && (q & 15) < 8) {
;         const int pn = q >> 4, c = (q & 15) * 8 + pn;
;         const float* pa = PART + ((size_t)(2 * c) * 256 + (m & 255)) * 256 + 4 * lane;
;         const f32x4 a = *(const f32x4*)pa, b = *(const f32x4*)(pa + 65536);
;         u32x2 w; w.x = cvt_pk_bf16(a.x + b.x, a.y + b.y); w.y = cvt_pk_bf16(a.z + b.z, a.w + b.w);
; #pragma unroll
;         for (int j = 0; j < 8; ++j) if (j == pn) y[j] = w;
;     }
; template <bool XIN_BF, bool XOUT_BF>
; __device__ __forceinline__ void norm_pass(const float* xp, const float* xs, const bf16_t* xbin, const bf16_t* Y, const float* post, float scale, const float* pre, float* X, bf16_t* xbout, bf16_t* XN, int gw, int NGW, int lane, const float* PART = nullptr) {
;     ...
;     for (int m = gw; m < M; m += NGW) {
;         f32x4 vn[8]; u32x2 yn[8];
;         const int mn = m + NGW < M ? m + NGW : m;
;         norm_load_x<XIN_BF, XOUT_BF>(xp, xs, xbin, mn, lane, vn); norm_load_y(Y, PART, mn, lane, yn);
.LBB0_1162:
	s_waitcnt vmcnt(23)
	v_lshlrev_b32_e32 v104, 16, v74
	v_and_b32_e32 v105, 0xffff0000, v74
	v_lshlrev_b32_e32 v106, 16, v75
	v_and_b32_e32 v107, 0xffff0000, v75
	s_waitcnt vmcnt(22)
	v_lshlrev_b32_e32 v100, 16, v72
	v_and_b32_e32 v101, 0xffff0000, v72
	v_lshlrev_b32_e32 v102, 16, v73
	v_and_b32_e32 v103, 0xffff0000, v73
	s_waitcnt vmcnt(21)
	v_lshlrev_b32_e32 v96, 16, v70
	v_and_b32_e32 v97, 0xffff0000, v70
	v_lshlrev_b32_e32 v98, 16, v71
	v_and_b32_e32 v99, 0xffff0000, v71
	s_waitcnt vmcnt(20)
	v_lshlrev_b32_e32 v92, 16, v68
	v_and_b32_e32 v93, 0xffff0000, v68
	v_lshlrev_b32_e32 v94, 16, v69
	v_and_b32_e32 v95, 0xffff0000, v69
	s_waitcnt vmcnt(19)
	v_lshlrev_b32_e32 v88, 16, v66
	v_and_b32_e32 v89, 0xffff0000, v66
	v_lshlrev_b32_e32 v90, 16, v67
	v_and_b32_e32 v91, 0xffff0000, v67
	s_waitcnt vmcnt(18)
	v_lshlrev_b32_e32 v84, 16, v64
	v_and_b32_e32 v85, 0xffff0000, v64
	v_lshlrev_b32_e32 v86, 16, v65
	v_and_b32_e32 v87, 0xffff0000, v65
	s_waitcnt vmcnt(17)
	v_lshlrev_b32_e32 v80, 16, v62
	v_and_b32_e32 v81, 0xffff0000, v62
	v_lshlrev_b32_e32 v82, 16, v63
	v_and_b32_e32 v83, 0xffff0000, v63
	s_waitcnt vmcnt(16)
	v_lshlrev_b32_e32 v76, 16, v54
	v_and_b32_e32 v77, 0xffff0000, v54
	v_lshlrev_b32_e32 v78, 16, v55
	v_and_b32_e32 v79, 0xffff0000, v55
	v_lshl_add_u64 v[42:43], v[42:43], 0, s[10:11]
	s_andn2_b64 vcc, exec, s[12:13]
	s_waitcnt vmcnt(15)
	v_mov_b64_e32 v[40:41], v[46:47]
	s_waitcnt vmcnt(14)
	v_mov_b32_e32 v32, v44
	v_mov_b32_e32 v33, v45
	s_waitcnt vmcnt(13)
	v_mov_b32_e32 v16, v48
	v_mov_b32_e32 v17, v49
	s_waitcnt vmcnt(12)
	v_mov_b32_e32 v14, v50
	v_mov_b32_e32 v15, v51
	s_waitcnt vmcnt(11)
	v_mov_b32_e32 v8, v52
	v_mov_b32_e32 v9, v53
	s_waitcnt vmcnt(10)
	v_mov_b32_e32 v6, v56
	v_mov_b32_e32 v7, v57
	s_waitcnt vmcnt(9)
	v_mov_b32_e32 v4, v58
	v_mov_b32_e32 v5, v59
	s_waitcnt vmcnt(8)
	v_mov_b32_e32 v2, v60
	v_mov_b32_e32 v3, v61
	s_cbranch_vccz .LBB0_1196
.LBB0_1163:
	s_mov_b32 s2, s19
	s_add_i32 s19, s19, s72
	s_cmp_gt_i32 s19, 0x87ff
	s_cselect_b64 s[12:13], -1, 0
	s_cmp_lt_i32 s19, 0x8800
	s_cselect_b32 s6, s19, s2
	s_ashr_i32 s7, s6, 31
	s_lshl_b64 s[14:15], s[6:7], 12
	v_lshl_add_u64 v[44:45], v[10:11], 0, s[14:15]
	v_lshl_add_u64 v[108:109], v[12:13], 0, s[14:15]
	global_load_dwordx2 v[74:75], v[44:45], off nt
	global_load_dwordx2 v[72:73], v[44:45], off offset:512 nt
	global_load_dwordx2 v[70:71], v[44:45], off offset:1024 nt
	global_load_dwordx2 v[68:69], v[44:45], off offset:1536 nt
	global_load_dwordx2 v[66:67], v[44:45], off offset:2048 nt
	global_load_dwordx2 v[64:65], v[44:45], off offset:2560 nt
	global_load_dwordx2 v[62:63], v[44:45], off offset:3072 nt
	global_load_dwordx2 v[54:55], v[44:45], off offset:3584 nt
	global_load_dwordx2 v[46:47], v[108:109], off nt
	s_nop 0
	global_load_dwordx2 v[44:45], v[108:109], off offset:512 nt
	global_load_dwordx2 v[48:49], v[108:109], off offset:1024 nt
	global_load_dwordx2 v[50:51], v[108:109], off offset:1536 nt
	global_load_dwordx2 v[52:53], v[108:109], off offset:2048 nt
	global_load_dwordx2 v[56:57], v[108:109], off offset:2560 nt
	global_load_dwordx2 v[58:59], v[108:109], off offset:3072 nt
	global_load_dwordx2 v[60:61], v[108:109], off offset:3584 nt
	s_ashr_i32 s2, s6, 8
	s_cmp_lt_i32 s2, 16
	s_cbranch_scc1 .LBB0_1194
	s_bfe_u32 s7, s6, 0x40008
	s_cmp_gt_u32 s7, 7
	s_cbranch_scc1 .LBB0_1194
	s_add_i32 s21, s2, -16
	s_lshr_b32 s20, s21, 4
	s_lshl_b32 s2, s7, 4
	s_lshl_b32 s7, s20, 1
	s_add_i32 s2, s7, s2
	s_lshl_b64 s[14:15], s[2:3], 18
	v_readlane_b32 s2, v236, 10
	s_add_u32 s2, s2, s14
	v_readlane_b32 s7, v236, 11
	s_addc_u32 s7, s7, s15
	s_lshl_b32 s6, s6, 10
	s_and_b32 s6, s6, 0x3fc00
	s_add_u32 s6, s2, s6
	s_addc_u32 s7, s7, 0
	v_lshl_add_u64 v[108:109], s[6:7], 0, v[0:1]
	v_add_co_u32_e32 v108, vcc, s16, v108
	s_cmp_lt_u32 s21, 16
	s_nop 0
	v_addc_co_u32_e32 v109, vcc, 0, v109, vcc
	global_load_dwordx4 v[118:121], v0, s[6:7]
	global_load_dwordx4 v[122:125], v[108:109], off
	s_cselect_b64 s[6:7], -1, 0
	s_cmp_lt_i32 s20, 4
	s_mov_b64 s[14:15], -1
	s_nop 0
	s_waitcnt vmcnt(0)
	v_pk_add_f32 v[120:121], v[120:121], v[124:125]
	v_pk_add_f32 v[108:109], v[118:119], v[122:123]
	s_nop 0
	v_cvt_pk_bf16_f32 v108, v108, v109
	v_cvt_pk_bf16_f32 v109, v120, v121
	s_cbranch_scc1 .LBB0_1181
	s_cmp_lt_i32 s20, 6
	s_cbranch_scc1 .LBB0_1174
	s_cmp_lt_i32 s20, 7
	s_cbranch_scc1 .LBB0_1171
	s_cmp_eq_u32 s20, 7
	v_mov_b32_e32 v117, v61
	v_mov_b32_e32 v118, v60
	s_cbranch_scc0 .LBB0_1170
	v_mov_b32_e32 v117, v109
	v_mov_b32_e32 v118, v108

; __device__ __forceinline__ unsigned cvt_pk_bf16(float lo, float hi) { const f32x2_cv v = {lo, hi}; return __builtin_bit_cast(unsigned, __builtin_convertvector(v, bf16x2_cv)); }
; __device__ __forceinline__ float bf_lo(unsigned u) { return __uint_as_float(u << 16); }
; __device__ __forceinline__ float bf_hi(unsigned u) { return __uint_as_float(u & 0xffff0000u); }
; template <bool XIN_BF, bool XOUT_BF>
; __device__ __forceinline__ void norm_pass(const float* xp, const float* xs, const bf16_t* xbin, const bf16_t* Y, const float* post, float scale, const float* pre, float* X, bf16_t* xbout, bf16_t* XN, int gw, int NGW, int lane, const float* PART = nullptr) {
;     ...
;         float s = 0.f;
; #pragma unroll
;         for (int j = 0; j < 8; ++j) { const float a = bf_lo(y[j].x), b = bf_hi(y[j].x), c = bf_lo(y[j].y), d = bf_hi(y[j].y); s += (a * a + b * b) + (c * c + d * d); }
;         const float rs = rsqrtf(wave_sum(s) * (1.f / D) + EPS) * scale; float s2 = 0.f;
; #pragma unroll
;         for (int j = 0; j < 8; ++j) { const f32x4 g = ((const f32x4*)post + lane)[64 * j];
;             v[j].x += bf_lo(y[j].x) * rs * g.x; v[j].y += bf_hi(y[j].x) * rs * g.y; v[j].z += bf_lo(y[j].y) * rs * g.z; v[j].w += bf_hi(y[j].y) * rs * g.w;
;             s2 += (v[j].x * v[j].x + v[j].y * v[j].y) + (v[j].z * v[j].z + v[j].w * v[j].w);
;             if (XOUT_BF) { u32x2 w; w.x = cvt_pk_bf16(v[j].x, v[j].y); w.y = cvt_pk_bf16(v[j].z, v[j].w); __builtin_nontemporal_store(w, &((u32x2*)(xbout + (size_t)m * D) + lane)[64 * j]); }
;             else __builtin_nontemporal_store(v[j], &((f32x4*)(X + (size_t)m * D) + lane)[64 * j]); }
.LBB0_1194:
	s_nop 0
	s_nop 0
	v_lshlrev_b32_e32 v122, 16, v41
	v_and_b32_e32 v123, 0xffff0000, v41
	s_nop 0
	v_and_b32_e32 v41, 0xffff0000, v33
	v_lshlrev_b32_e32 v108, 16, v40
	v_and_b32_e32 v109, 0xffff0000, v40
	v_lshlrev_b32_e32 v40, 16, v33
	v_and_b32_e32 v125, 0xffff0000, v32
	v_mov_b32_e32 v126, v123
	v_mov_b32_e32 v127, v41
	v_lshlrev_b32_e32 v124, 16, v32
	v_mov_b32_e32 v32, v122
	v_mov_b32_e32 v33, v40
	v_pk_mul_f32 v[126:127], v[126:127], v[126:127]
	v_mov_b32_e32 v130, v109
	v_mov_b32_e32 v131, v125
	v_pk_fma_f32 v[32:33], v[32:33], v[32:33], v[126:127]
	v_mov_b32_e32 v126, v108
	v_mov_b32_e32 v127, v124
	v_pk_mul_f32 v[130:131], v[130:131], v[130:131]
	s_nop 0
	v_and_b32_e32 v137, 0xffff0000, v14
	v_pk_fma_f32 v[126:127], v[126:127], v[126:127], v[130:131]
	v_and_b32_e32 v131, 0xffff0000, v16
	v_pk_add_f32 v[32:33], v[126:127], v[32:33]
	v_and_b32_e32 v127, 0xffff0000, v17
	v_lshlrev_b32_e32 v126, 16, v17
	v_lshlrev_b32_e32 v130, 16, v16
	v_mov_b32_e32 v132, v131
	v_mov_b32_e32 v133, v127
	v_mov_b32_e32 v16, v130
	v_mov_b32_e32 v17, v126
	v_pk_mul_f32 v[132:133], v[132:133], v[132:133]
	v_lshlrev_b32_e32 v136, 16, v14
	v_pk_fma_f32 v[16:17], v[16:17], v[16:17], v[132:133]
	v_and_b32_e32 v133, 0xffff0000, v15
	v_lshlrev_b32_e32 v132, 16, v15
	v_mul_f32_e32 v134, v133, v133
	v_mul_f32_e32 v14, v137, v137
	s_nop 0
	v_lshlrev_b32_e32 v138, 16, v9
	v_and_b32_e32 v139, 0xffff0000, v9
	v_lshlrev_b32_e32 v142, 16, v8
	v_and_b32_e32 v143, 0xffff0000, v8
	v_pk_add_f32 v[32:33], v[32:33], v[32:33] op_sel:[0,1] op_sel_hi:[1,0]
	v_pk_add_f32 v[16:17], v[16:17], v[16:17] op_sel:[0,1] op_sel_hi:[1,0]
	v_pk_fma_f32 v[134:135], v[132:133], v[132:133], v[134:135] op_sel_hi:[1,1,0]
	v_pk_fma_f32 v[14:15], v[136:137], v[136:137], v[14:15] op_sel_hi:[1,1,0]
	v_pk_mul_f32 v[140:141], v[138:139], v[138:139]
	v_pk_mul_f32 v[8:9], v[142:143], v[142:143]
	v_mov_b32_e32 v15, v140
	v_mov_b32_e32 v135, v141
	v_mov_b32_e32 v33, v8
	v_mov_b32_e32 v17, v9
	v_pk_add_f32 v[14:15], v[14:15], v[134:135]
	v_pk_add_f32 v[8:9], v[32:33], v[16:17]
	s_nop 0
	v_and_b32_e32 v135, 0xffff0000, v7
	v_and_b32_e32 v141, 0xffff0000, v6
	v_pk_add_f32 v[8:9], v[8:9], v[14:15]
	v_lshlrev_b32_e32 v134, 16, v7
	v_lshlrev_b32_e32 v140, 16, v6
	v_mov_b32_e32 v14, v141
	v_mov_b32_e32 v15, v135
	v_mov_b32_e32 v6, v140
	v_mov_b32_e32 v7, v134
	v_pk_mul_f32 v[14:15], v[14:15], v[14:15]
	s_nop 0
	v_and_b32_e32 v145, 0xffff0000, v5
	v_and_b32_e32 v147, 0xffff0000, v4
	v_pk_fma_f32 v[6:7], v[6:7], v[6:7], v[14:15]
	v_lshlrev_b32_e32 v144, 16, v5
	v_mul_f32_e32 v14, v145, v145
	v_lshlrev_b32_e32 v146, 16, v4
	v_mul_f32_e32 v4, v147, v147
	s_nop 0
	v_lshlrev_b32_e32 v148, 16, v3
	v_and_b32_e32 v149, 0xffff0000, v3
	v_lshlrev_b32_e32 v150, 16, v2
	v_and_b32_e32 v151, 0xffff0000, v2
	v_pk_add_f32 v[8:9], v[8:9], v[8:9] op_sel:[0,1] op_sel_hi:[1,0]
	v_pk_add_f32 v[6:7], v[6:7], v[6:7] op_sel:[0,1] op_sel_hi:[1,0]
	v_pk_fma_f32 v[14:15], v[144:145], v[144:145], v[14:15] op_sel_hi:[1,1,0]
	v_pk_fma_f32 v[4:5], v[146:147], v[146:147], v[4:5] op_sel_hi:[1,1,0]
	v_pk_mul_f32 v[16:17], v[148:149], v[148:149]
	v_pk_mul_f32 v[2:3], v[150:151], v[150:151]
	v_mov_b32_e32 v5, v16
	v_mov_b32_e32 v15, v17
	v_mov_b32_e32 v9, v2
	v_mov_b32_e32 v7, v3
	v_pk_add_f32 v[4:5], v[4:5], v[14:15]
	v_pk_add_f32 v[2:3], v[8:9], v[6:7]
	s_nop 0
	v_pk_add_f32 v[2:3], v[2:3], v[4:5]
	s_nop 0
	v_add_f32_e32 v2, v2, v3
	ds_bpermute_b32 v3, v110, v2
	s_waitcnt lgkmcnt(0)
	v_add_f32_e32 v2, v2, v3
	ds_bpermute_b32 v3, v111, v2
	s_waitcnt lgkmcnt(0)
	v_add_f32_e32 v2, v2, v3
	ds_bpermute_b32 v3, v112, v2
	s_waitcnt lgkmcnt(0)
	v_add_f32_e32 v2, v2, v3
	ds_bpermute_b32 v3, v113, v2
	s_waitcnt lgkmcnt(0)
	v_add_f32_e32 v2, v2, v3
	ds_bpermute_b32 v3, v114, v2
	s_waitcnt lgkmcnt(0)
	v_add_f32_e32 v2, v2, v3
	ds_bpermute_b32 v3, v115, v2
	s_waitcnt lgkmcnt(0)
	v_add_f32_e32 v2, v2, v3
	v_fmamk_f32 v2, v2, 0x3a000000, v116
	v_mul_f32_e32 v3, 0x4b800000, v2
	v_cmp_gt_f32_e32 vcc, s17, v2
	s_nop 1
	v_cndmask_b32_e32 v2, v2, v3, vcc
	v_rsq_f32_e32 v2, v2
	s_nop 0
	v_mul_f32_e32 v3, 0x45800000, v2
	v_cndmask_b32_e32 v2, v2, v3, vcc
	v_mul_f32_e32 v152, 0.5, v2
	v_pk_mul_f32 v[2:3], v[152:153], v[108:109] op_sel_hi:[0,1]
	s_nop 0
	v_pk_fma_f32 v[108:109], v[156:157], v[2:3], v[104:105]
	v_pk_mul_f32 v[2:3], v[152:153], v[122:123] op_sel_hi:[0,1]
	v_pk_fma_f32 v[104:105], v[158:159], v[2:3], v[106:107]
	v_cvt_pk_bf16_f32 v2, v108, v109
	v_cvt_pk_bf16_f32 v3, v104, v105
	global_store_dwordx2 v[42:43], v[2:3], off offset:-3584 nt
	s_nop 0
	v_pk_mul_f32 v[6:7], v[152:153], v[124:125] op_sel_hi:[0,1]
	v_pk_mul_f32 v[8:9], v[152:153], v[40:41] op_sel_hi:[0,1]
	s_andn2_b64 vcc, exec, s[4:5]
	s_nop 0
	v_pk_fma_f32 v[100:101], v[160:161], v[6:7], v[100:101]
	v_pk_fma_f32 v[102:103], v[162:163], v[8:9], v[102:103]
	v_cvt_pk_bf16_f32 v2, v100, v101
	v_cvt_pk_bf16_f32 v3, v102, v103
	global_store_dwordx2 v[42:43], v[2:3], off offset:-3072 nt
	s_nop 0
	v_pk_mul_f32 v[6:7], v[152:153], v[130:131] op_sel_hi:[0,1]
	v_pk_mul_f32 v[8:9], v[152:153], v[126:127] op_sel_hi:[0,1]
	s_nop 0
	v_pk_fma_f32 v[96:97], v[164:165], v[6:7], v[96:97]
	v_pk_fma_f32 v[98:99], v[166:167], v[8:9], v[98:99]
	v_cvt_pk_bf16_f32 v2, v96, v97
	v_cvt_pk_bf16_f32 v3, v98, v99
	global_store_dwordx2 v[42:43], v[2:3], off offset:-2560 nt
	s_nop 0
	v_pk_mul_f32 v[6:7], v[152:153], v[136:137] op_sel_hi:[0,1]
	v_pk_mul_f32 v[8:9], v[152:153], v[132:133] op_sel_hi:[0,1]
	s_nop 0
	v_pk_fma_f32 v[32:33], v[168:169], v[6:7], v[92:93]
	v_pk_fma_f32 v[40:41], v[170:171], v[8:9], v[94:95]
	v_cvt_pk_bf16_f32 v2, v32, v33
	v_cvt_pk_bf16_f32 v3, v40, v41
	global_store_dwordx2 v[42:43], v[2:3], off offset:-2048 nt
; __device__ __forceinline__ unsigned cvt_pk_bf16(float lo, float hi) { const f32x2_cv v = {lo, hi}; return __builtin_bit_cast(unsigned, __builtin_convertvector(v, bf16x2_cv)); }
; __device__ __forceinline__ float bf_lo(unsigned u) { return __uint_as_float(u << 16); }
; __device__ __forceinline__ float bf_hi(unsigned u) { return __uint_as_float(u & 0xffff0000u); }
; template <bool XIN_BF, bool XOUT_BF>
; __device__ __forceinline__ void norm_pass(const float* xp, const float* xs, const bf16_t* xbin, const bf16_t* Y, const float* post, float scale, const float* pre, float* X, bf16_t* xbout, bf16_t* XN, int gw, int NGW, int lane, const float* PART = nullptr) {
;     ...
;         for (int j = 0; j < 8; ++j) { const f32x4 g = ((const f32x4*)post + lane)[64 * j];
;             v[j].x += bf_lo(y[j].x) * rs * g.x; v[j].y += bf_hi(y[j].x) * rs * g.y; v[j].z += bf_lo(y[j].y) * rs * g.z; v[j].w += bf_hi(y[j].y) * rs * g.w;
;             s2 += (v[j].x * v[j].x + v[j].y * v[j].y) + (v[j].z * v[j].z + v[j].w * v[j].w);
;             if (XOUT_BF) { u32x2 w; w.x = cvt_pk_bf16(v[j].x, v[j].y); w.y = cvt_pk_bf16(v[j].z, v[j].w); __builtin_nontemporal_store(w, &((u32x2*)(xbout + (size_t)m * D) + lane)[64 * j]); }
;             else __builtin_nontemporal_store(v[j], &((f32x4*)(X + (size_t)m * D) + lane)[64 * j]); }
	s_nop 0
	v_pk_mul_f32 v[6:7], v[152:153], v[142:143] op_sel_hi:[0,1]
	v_pk_mul_f32 v[8:9], v[152:153], v[138:139] op_sel_hi:[0,1]
	s_nop 0
	v_pk_fma_f32 v[14:15], v[172:173], v[6:7], v[88:89]
	v_pk_fma_f32 v[16:17], v[174:175], v[8:9], v[90:91]
	v_cvt_pk_bf16_f32 v2, v14, v15
	v_cvt_pk_bf16_f32 v3, v16, v17
	global_store_dwordx2 v[42:43], v[2:3], off offset:-1536 nt
	s_nop 0
	v_pk_mul_f32 v[6:7], v[152:153], v[140:141] op_sel_hi:[0,1]
	v_pk_mul_f32 v[8:9], v[152:153], v[134:135] op_sel_hi:[0,1]
	s_nop 0
	v_pk_fma_f32 v[6:7], v[6:7], v[176:177], v[84:85]
	v_pk_fma_f32 v[8:9], v[8:9], v[178:179], v[86:87]
	v_cvt_pk_bf16_f32 v2, v6, v7
	v_cvt_pk_bf16_f32 v3, v8, v9
	global_store_dwordx2 v[42:43], v[2:3], off offset:-1024 nt
	s_nop 0
	v_pk_mul_f32 v[84:85], v[152:153], v[146:147] op_sel_hi:[0,1]
	v_pk_mul_f32 v[86:87], v[152:153], v[144:145] op_sel_hi:[0,1]
	s_nop 0
	v_pk_fma_f32 v[2:3], v[84:85], v[180:181], v[80:81]
	v_pk_fma_f32 v[4:5], v[86:87], v[182:183], v[82:83]
	v_cvt_pk_bf16_f32 v80, v2, v3
	v_cvt_pk_bf16_f32 v81, v4, v5
	global_store_dwordx2 v[42:43], v[80:81], off offset:-512 nt
	s_nop 0
	v_pk_mul_f32 v[84:85], v[152:153], v[150:151] op_sel_hi:[0,1]
	v_pk_mul_f32 v[86:87], v[152:153], v[148:149] op_sel_hi:[0,1]
	s_nop 0
	v_pk_fma_f32 v[80:81], v[84:85], v[184:185], v[76:77]
	v_pk_fma_f32 v[76:77], v[86:87], v[186:187], v[78:79]
	v_cvt_pk_bf16_f32 v78, v80, v81
	v_cvt_pk_bf16_f32 v79, v76, v77
	global_store_dwordx2 v[42:43], v[78:79], off nt
	s_cbranch_vccnz .LBB0_1162
; __device__ __forceinline__ unsigned cvt_pk_bf16(float lo, float hi) { const f32x2_cv v = {lo, hi}; return __builtin_bit_cast(unsigned, __builtin_convertvector(v, bf16x2_cv)); }
; template <bool XIN_BF, bool XOUT_BF>
; __device__ __forceinline__ void norm_pass(const float* xp, const float* xs, const bf16_t* xbin, const bf16_t* Y, const float* post, float scale, const float* pre, float* X, bf16_t* xbout, bf16_t* XN, int gw, int NGW, int lane, const float* PART = nullptr) {
;     ...
;             s2 += (v[j].x * v[j].x + v[j].y * v[j].y) + (v[j].z * v[j].z + v[j].w * v[j].w);
;             if (XOUT_BF) { u32x2 w; w.x = cvt_pk_bf16(v[j].x, v[j].y); w.y = cvt_pk_bf16(v[j].z, v[j].w); __builtin_nontemporal_store(w, &((u32x2*)(xbout + (size_t)m * D) + lane)[64 * j]); }
;             else __builtin_nontemporal_store(v[j], &((f32x4*)(X + (size_t)m * D) + lane)[64 * j]); }
;         if (pre) {
;             const float r2 = rsqrtf(wave_sum(s2) * (1.f / D) + EPS); u32x2* o8 = (u32x2*)(XN + (size_t)m * D) + lane;
; #pragma unroll
;             for (int j = 0; j < 8; ++j) { const f32x4 g = ((const f32x4*)pre + lane)[64 * j]; u32x2 w; w.x = cvt_pk_bf16(v[j].x * r2 * g.x, v[j].y * r2 * g.y); w.y = cvt_pk_bf16(v[j].z * r2 * g.z, v[j].w * r2 * g.w); o8[64 * j] = w; }
;         }
	v_mov_b32_e32 v82, v109
	v_mov_b32_e32 v83, v101
	v_mov_b32_e32 v78, v108
	v_mov_b32_e32 v79, v100
	v_pk_mul_f32 v[82:83], v[82:83], v[82:83]
	v_mov_b32_e32 v84, v104
	v_mov_b32_e32 v85, v102
	v_pk_fma_f32 v[78:79], v[78:79], v[78:79], v[82:83]
	v_mov_b32_e32 v82, v105
	v_mov_b32_e32 v83, v103
	v_pk_mul_f32 v[84:85], v[84:85], v[84:85]
	v_pk_mul_f32 v[92:93], v[14:15], v[14:15]
	v_pk_fma_f32 v[82:83], v[82:83], v[82:83], v[84:85]
	v_pk_mov_b32 v[84:85], v[96:97], v[98:99] op_sel:[1,0]
	v_pk_add_f32 v[78:79], v[78:79], v[82:83]
	v_mov_b32_e32 v82, v96
	v_mov_b32_e32 v83, v99
	v_pk_mul_f32 v[84:85], v[84:85], v[84:85]
	v_pk_add_f32 v[78:79], v[78:79], v[78:79] op_sel_hi:[0,1]
	v_pk_fma_f32 v[82:83], v[82:83], v[82:83], v[84:85]
	v_mul_f32_e32 v78, v32, v32
	v_pk_add_f32 v[86:87], v[82:83], v[82:83] op_sel_hi:[0,1]
	s_nop 0
	v_pk_fma_f32 v[88:89], v[32:33], v[32:33], v[78:79] op_sel_hi:[1,1,0]
	v_mul_f32_e32 v78, v40, v40
	v_pk_fma_f32 v[90:91], v[40:41], v[40:41], v[78:79] op_sel_hi:[1,1,0]
	v_pk_mul_f32 v[94:95], v[16:17], v[16:17]
	v_mov_b32_e32 v88, v92
	v_mov_b32_e32 v90, v93
	v_mov_b32_e32 v86, v95
	v_mov_b32_e32 v95, v79
	v_pk_add_f32 v[88:89], v[88:89], v[90:91]
	v_pk_add_f32 v[78:79], v[86:87], v[94:95]
	v_mov_b32_e32 v86, v6
	v_pk_add_f32 v[78:79], v[88:89], v[78:79]
	v_pk_mov_b32 v[88:89], v[6:7], v[8:9] op_sel:[1,0]
	v_pk_add_f32 v[78:79], v[78:79], v[78:79] op_sel_hi:[0,1]
	v_mov_b32_e32 v87, v9
	v_pk_mul_f32 v[88:89], v[88:89], v[88:89]
	v_mul_f32_e32 v78, v2, v2
	v_pk_fma_f32 v[86:87], v[86:87], v[86:87], v[88:89]
	v_pk_fma_f32 v[88:89], v[2:3], v[2:3], v[78:79] op_sel_hi:[1,1,0]
	v_mul_f32_e32 v78, v4, v4
	v_pk_add_f32 v[86:87], v[86:87], v[86:87] op_sel_hi:[0,1]
	v_pk_fma_f32 v[90:91], v[4:5], v[4:5], v[78:79] op_sel_hi:[1,1,0]
	v_pk_mul_f32 v[92:93], v[80:81], v[80:81]
	v_pk_mul_f32 v[94:95], v[76:77], v[76:77]
	v_mov_b32_e32 v88, v92
	v_mov_b32_e32 v90, v93
	v_mov_b32_e32 v86, v95
	v_mov_b32_e32 v95, v79
	v_pk_add_f32 v[88:89], v[88:89], v[90:91]
	v_pk_add_f32 v[78:79], v[86:87], v[94:95]
	s_nop 0
	v_pk_add_f32 v[78:79], v[88:89], v[78:79]
	s_nop 0
	v_add_f32_e32 v78, v78, v79
	ds_bpermute_b32 v79, v110, v78
	s_waitcnt lgkmcnt(0)
	v_add_f32_e32 v78, v78, v79
	ds_bpermute_b32 v79, v111, v78
	s_waitcnt lgkmcnt(0)
	v_add_f32_e32 v78, v78, v79
	ds_bpermute_b32 v79, v112, v78
	s_waitcnt lgkmcnt(0)
	v_add_f32_e32 v78, v78, v79
	ds_bpermute_b32 v79, v113, v78
	s_waitcnt lgkmcnt(0)
	v_add_f32_e32 v78, v78, v79
	ds_bpermute_b32 v79, v114, v78
	s_waitcnt lgkmcnt(0)
	v_add_f32_e32 v78, v78, v79
	ds_bpermute_b32 v79, v115, v78
	s_waitcnt lgkmcnt(0)
	v_add_f32_e32 v78, v78, v79
	v_fmamk_f32 v78, v78, 0x3a000000, v116
	v_mul_f32_e32 v79, 0x4b800000, v78
	v_cmp_gt_f32_e32 vcc, s17, v78
	s_nop 1
	v_cndmask_b32_e32 v78, v78, v79, vcc
	v_rsq_f32_e32 v78, v78
	s_nop 0
	v_mul_f32_e32 v79, 0x45800000, v78
	v_cndmask_b32_e32 v78, v78, v79, vcc
	v_pk_mul_f32 v[86:87], v[108:109], v[78:79] op_sel_hi:[1,0]
	v_pk_mul_f32 v[88:89], v[104:105], v[78:79] op_sel_hi:[1,0]
	s_nop 0
	v_pk_mul_f32 v[82:83], v[188:189], v[86:87]
	v_pk_mul_f32 v[84:85], v[190:191], v[88:89]
	v_add_co_u32_e32 v86, vcc, s18, v42
	v_cvt_pk_bf16_f32 v82, v82, v83
	v_cvt_pk_bf16_f32 v83, v84, v85
	v_addc_co_u32_e32 v87, vcc, -1, v43, vcc
	global_store_dwordx2 v[86:87], v[82:83], off offset:-3584
	s_nop 0
	v_pk_mul_f32 v[88:89], v[100:101], v[78:79] op_sel_hi:[1,0]
	v_pk_mul_f32 v[90:91], v[102:103], v[78:79] op_sel_hi:[1,0]
	v_pk_mul_f32 v[32:33], v[32:33], v[78:79] op_sel_hi:[1,0]
	v_pk_mul_f32 v[40:41], v[40:41], v[78:79] op_sel_hi:[1,0]
	v_pk_mul_f32 v[14:15], v[14:15], v[78:79] op_sel_hi:[1,0]
	v_pk_mul_f32 v[16:17], v[16:17], v[78:79] op_sel_hi:[1,0]
	v_pk_mul_f32 v[6:7], v[6:7], v[78:79] op_sel_hi:[1,0]
	v_pk_mul_f32 v[8:9], v[8:9], v[78:79] op_sel_hi:[1,0]
	v_pk_mul_f32 v[2:3], v[2:3], v[78:79] op_sel_hi:[1,0]
	v_pk_mul_f32 v[4:5], v[4:5], v[78:79] op_sel_hi:[1,0]
	s_nop 0
	v_pk_mul_f32 v[82:83], v[192:193], v[88:89]
	v_pk_mul_f32 v[84:85], v[194:195], v[90:91]
	v_cvt_pk_bf16_f32 v82, v82, v83
	v_cvt_pk_bf16_f32 v83, v84, v85
	global_store_dwordx2 v[86:87], v[82:83], off offset:-3072
	s_nop 0
	v_pk_mul_f32 v[88:89], v[96:97], v[78:79] op_sel_hi:[1,0]
	v_pk_mul_f32 v[90:91], v[98:99], v[78:79] op_sel_hi:[1,0]
	s_nop 0
	v_pk_mul_f32 v[82:83], v[196:197], v[88:89]
	v_pk_mul_f32 v[84:85], v[198:199], v[90:91]
	v_cvt_pk_bf16_f32 v82, v82, v83
	v_cvt_pk_bf16_f32 v83, v84, v85
	global_store_dwordx2 v[86:87], v[82:83], off offset:-2560
	s_nop 0
	s_nop 0
	v_pk_mul_f32 v[32:33], v[200:201], v[32:33]
	v_pk_mul_f32 v[40:41], v[202:203], v[40:41]
	v_cvt_pk_bf16_f32 v32, v32, v33
	v_cvt_pk_bf16_f32 v33, v40, v41
	global_store_dwordx2 v[86:87], v[32:33], off offset:-2048
	s_nop 0
	s_nop 0
	v_pk_mul_f32 v[14:15], v[14:15], v[204:205]
	v_pk_mul_f32 v[16:17], v[16:17], v[206:207]
	v_cvt_pk_bf16_f32 v14, v14, v15
	v_cvt_pk_bf16_f32 v15, v16, v17
	global_store_dwordx2 v[86:87], v[14:15], off offset:-1536
	s_nop 0
	s_nop 0
	v_pk_mul_f32 v[6:7], v[6:7], v[208:209]
	v_pk_mul_f32 v[8:9], v[8:9], v[210:211]
	v_cvt_pk_bf16_f32 v6, v6, v7
	v_cvt_pk_bf16_f32 v7, v8, v9
	global_store_dwordx2 v[86:87], v[6:7], off offset:-1024
	s_nop 0
	s_nop 0
	v_pk_mul_f32 v[2:3], v[2:3], v[212:213]
	v_pk_mul_f32 v[4:5], v[4:5], v[214:215]
	v_cvt_pk_bf16_f32 v2, v2, v3
	v_cvt_pk_bf16_f32 v3, v4, v5
	global_store_dwordx2 v[86:87], v[2:3], off offset:-512
	s_nop 0
	v_pk_mul_f32 v[6:7], v[80:81], v[78:79] op_sel_hi:[1,0]
	v_pk_mul_f32 v[8:9], v[76:77], v[78:79] op_sel_hi:[1,0]
	s_nop 0
	v_pk_mul_f32 v[2:3], v[6:7], v[216:217]
	v_pk_mul_f32 v[4:5], v[8:9], v[218:219]
	v_cvt_pk_bf16_f32 v2, v2, v3
	v_cvt_pk_bf16_f32 v3, v4, v5
	global_store_dwordx2 v[86:87], v[2:3], off
	s_branch .LBB0_1162

; __device__ __forceinline__ float bf_lo(unsigned u) { return __uint_as_float(u << 16); }
; __device__ __forceinline__ float bf_hi(unsigned u) { return __uint_as_float(u & 0xffff0000u); }
; template <bool XIN_BF, bool XOUT_BF>
; __device__ __forceinline__ void norm_load_x(const float* xp, const float* xs, const bf16_t* xb, int m, int lane, f32x4 (&v)[8]) {
;     if (XIN_BF) { const u32x2* xr = (const u32x2*)(xb + (size_t)m * D) + lane;
; #pragma unroll
;         for (int j = 0; j < 8; ++j) { const u32x2 w = __builtin_nontemporal_load(&xr[64 * j]); v[j] = (f32x4){bf_lo(w.x), bf_hi(w.x), bf_lo(w.y), bf_hi(w.y)}; }
;     } else { const float* xrow = (m < MP) ? xp + (size_t)m * D : xs + (size_t)(m - MP) * D; const f32x4* xr = (const f32x4*)xrow + lane;
; #pragma unroll
;         for (int j = 0; j < 8; ++j) v[j] = __builtin_nontemporal_load(&xr[64 * j]); }
; }
; template <bool XIN_BF, bool XOUT_BF>
; __device__ __forceinline__ void norm_pass(const float* xp, const float* xs, const bf16_t* xbin, const bf16_t* Y, const float* post, float scale, const float* pre, float* X, bf16_t* xbout, bf16_t* XN, int gw, int NGW, int lane, const float* PART = nullptr) {
;     f32x4 v[8]; u32x2 y[8];
;     norm_load_x<XIN_BF, XOUT_BF>(xp, xs, xbin, gw, lane, v); norm_load_y(Y, PART, gw, lane, y);
;     for (int m = gw; m < M; m += NGW) {
;         f32x4 vn[8]; u32x2 yn[8];
;         const int mn = m + NGW < M ? m + NGW : m;
;         norm_load_x<XIN_BF, XOUT_BF>(xp, xs, xbin, mn, lane, vn); norm_load_y(Y, PART, mn, lane, yn);
.LBB0_1321:
	s_cmp_lt_i32 s88, 16
	s_cselect_b64 s[0:1], -1, 0
	s_and_b64 s[0:1], s[0:1], s[2:3]
	s_andn2_b64 vcc, exec, s[0:1]
	s_cbranch_vccnz .LBB0_1325
	s_cmp_gt_i32 s74, 0x87ff
	s_cbranch_scc1 .LBB0_1325
	s_ashr_i32 s75, s74, 31
	s_lshl_b64 s[0:1], s[74:75], 12
	s_add_u32 s2, s94, s0
	s_addc_u32 s3, s95, s1
	s_add_u32 s0, s68, s0
	s_waitcnt vmcnt(0)
	v_lshlrev_b32_e32 v0, 3, v128
	s_addc_u32 s1, s69, s1
	global_load_dwordx2 v[2:3], v0, s[0:1] nt
	global_load_dwordx2 v[8:9], v0, s[0:1] offset:512 nt
	global_load_dwordx2 v[10:11], v0, s[0:1] offset:1024 nt
	global_load_dwordx2 v[12:13], v0, s[0:1] offset:1536 nt
	global_load_dwordx2 v[14:15], v0, s[0:1] offset:2048 nt
	global_load_dwordx2 v[16:17], v0, s[0:1] offset:2560 nt
	global_load_dwordx2 v[18:19], v0, s[0:1] offset:3072 nt
	global_load_dwordx2 v[20:21], v0, s[0:1] offset:3584 nt
	global_load_dwordx2 v[52:53], v0, s[2:3] offset:3584 nt
	global_load_dwordx2 v[54:55], v0, s[2:3] offset:3072 nt
	global_load_dwordx2 v[56:57], v0, s[2:3] offset:2560 nt
	global_load_dwordx2 v[58:59], v0, s[2:3] offset:2048 nt
	global_load_dwordx2 v[60:61], v0, s[2:3] offset:1536 nt
	global_load_dwordx2 v[62:63], v0, s[2:3] offset:1024 nt
	global_load_dwordx2 v[64:65], v0, s[2:3] offset:512 nt
	global_load_dwordx2 v[66:67], v0, s[2:3] nt
	v_mbcnt_lo_u32_b32 v22, -1, 0
	v_mbcnt_hi_u32_b32 v22, -1, v22
	v_and_b32_e32 v23, 64, v22
	v_mov_b32_e32 v1, 0
	v_xor_b32_e32 v24, 1, v22
	v_add_u32_e32 v23, 64, v23
	s_load_dwordx2 s[0:1], s[42:43], 0xd0
	v_lshl_add_u64 v[4:5], s[68:69], 0, v[0:1]
	v_lshl_add_u64 v[6:7], s[94:95], 0, v[0:1]
	v_xor_b32_e32 v0, 2, v22
	v_cmp_lt_i32_e32 vcc, v24, v23
	v_xor_b32_e32 v25, 4, v22
	v_xor_b32_e32 v26, 8, v22
	v_cndmask_b32_e32 v24, v22, v24, vcc
	v_cmp_lt_i32_e32 vcc, v0, v23
	v_xor_b32_e32 v27, 16, v22
	v_xor_b32_e32 v28, 32, v22
	v_cndmask_b32_e32 v0, v22, v0, vcc
	v_cmp_lt_i32_e32 vcc, v25, v23
	v_lshlrev_b32_e32 v73, 2, v0
	v_lshlrev_b32_e32 v0, 4, v128
	v_cndmask_b32_e32 v25, v22, v25, vcc
	v_cmp_lt_i32_e32 vcc, v26, v23
	s_mov_b64 s[2:3], 0x1400
	v_lshlrev_b32_e32 v72, 2, v24
	v_cndmask_b32_e32 v26, v22, v26, vcc
	v_cmp_lt_i32_e32 vcc, v27, v23
	v_lshlrev_b32_e32 v74, 2, v25
	v_lshlrev_b32_e32 v75, 2, v26
	v_cndmask_b32_e32 v27, v22, v27, vcc
	v_cmp_lt_i32_e32 vcc, v28, v23
	v_lshlrev_b32_e32 v76, 2, v27
	v_mov_b32_e32 v78, 0x358637bd
	v_cndmask_b32_e32 v22, v22, v28, vcc
	v_lshlrev_b32_e32 v77, 2, v22
	s_mov_b32 s4, 0x800000
	s_waitcnt vmcnt(15)
	v_lshlrev_b32_e32 v48, 16, v2
	s_waitcnt vmcnt(14)
	v_lshlrev_b32_e32 v44, 16, v8
	v_and_b32_e32 v45, 0xffff0000, v8
	s_waitcnt vmcnt(12)
	v_lshlrev_b32_e32 v36, 16, v12
	v_and_b32_e32 v37, 0xffff0000, v12
	v_lshlrev_b32_e32 v38, 16, v13
	v_and_b32_e32 v39, 0xffff0000, v13
	s_waitcnt lgkmcnt(0)
	v_lshl_add_u64 v[12:13], s[0:1], 0, v[0:1]
	s_waitcnt vmcnt(10)
	v_lshlrev_b32_e32 v28, 16, v16
	v_and_b32_e32 v29, 0xffff0000, v16
	v_lshlrev_b32_e32 v30, 16, v17
	v_and_b32_e32 v31, 0xffff0000, v17
	v_lshl_add_u64 v[16:17], v[12:13], 0, s[2:3]
	s_mov_b64 s[2:3], 0x1800
	s_waitcnt vmcnt(9)
	v_lshlrev_b32_e32 v24, 16, v18
	v_and_b32_e32 v25, 0xffff0000, v18
	v_lshlrev_b32_e32 v26, 16, v19
	v_and_b32_e32 v27, 0xffff0000, v19
	v_lshl_add_u64 v[18:19], v[12:13], 0, s[2:3]
	s_mov_b64 s[2:3], 0x1c00
	v_lshlrev_b32_e32 v46, 16, v9
	v_and_b32_e32 v47, 0xffff0000, v9
	v_lshlrev_b32_e32 v40, 16, v10
	v_and_b32_e32 v41, 0xffff0000, v10
	v_lshlrev_b32_e32 v42, 16, v11
	v_and_b32_e32 v43, 0xffff0000, v11
	s_waitcnt vmcnt(8)
	v_lshlrev_b32_e32 v8, 16, v20
	v_and_b32_e32 v9, 0xffff0000, v20
	v_lshlrev_b32_e32 v10, 16, v21
	v_and_b32_e32 v11, 0xffff0000, v21
	v_lshl_add_u64 v[20:21], v[12:13], 0, s[2:3]
	s_lshl_b64 s[2:3], s[74:75], 13
	s_add_u32 s2, s84, s2
	s_addc_u32 s3, s85, s3
	s_mov_b64 s[0:1], 0x1000
	v_lshl_add_u64 v[0:1], s[2:3], 0, v[0:1]
	s_ashr_i32 s73, s72, 31
	v_and_b32_e32 v49, 0xffff0000, v2
	v_lshlrev_b32_e32 v50, 16, v3
	v_and_b32_e32 v51, 0xffff0000, v3
	v_lshlrev_b32_e32 v32, 16, v14
	v_and_b32_e32 v33, 0xffff0000, v14
	v_lshlrev_b32_e32 v34, 16, v15
	v_and_b32_e32 v35, 0xffff0000, v15
	v_lshl_add_u64 v[14:15], v[12:13], 0, s[0:1]
	v_lshl_add_u64 v[22:23], v[0:1], 0, s[0:1]
	s_lshl_b64 s[2:3], s[72:73], 13
	global_load_dwordx4 v[136:139], v[12:13], off
	global_load_dwordx4 v[140:143], v[12:13], off offset:1024
	global_load_dwordx4 v[144:147], v[12:13], off offset:2048
	global_load_dwordx4 v[148:151], v[12:13], off offset:3072
	global_load_dwordx4 v[152:155], v[14:15], off
	global_load_dwordx4 v[156:159], v[16:17], off
	global_load_dwordx4 v[160:163], v[18:19], off
	global_load_dwordx4 v[164:167], v[20:21], off
; __device__ __forceinline__ float bf_lo(unsigned u) { return __uint_as_float(u << 16); }
; __device__ __forceinline__ float bf_hi(unsigned u) { return __uint_as_float(u & 0xffff0000u); }
; template <bool XIN_BF, bool XOUT_BF>
; __device__ __forceinline__ void norm_pass(const float* xp, const float* xs, const bf16_t* xbin, const bf16_t* Y, const float* post, float scale, const float* pre, float* X, bf16_t* xbout, bf16_t* XN, int gw, int NGW, int lane, const float* PART = nullptr) {
;     ...
;     for (int m = gw; m < M; m += NGW) {
;         f32x4 vn[8]; u32x2 yn[8];
;         const int mn = m + NGW < M ? m + NGW : m;
;         norm_load_x<XIN_BF, XOUT_BF>(xp, xs, xbin, mn, lane, vn); norm_load_y(Y, PART, mn, lane, yn);
;         float s = 0.f;
; #pragma unroll
;         for (int j = 0; j < 8; ++j) { const float a = bf_lo(y[j].x), b = bf_hi(y[j].x), c = bf_lo(y[j].y), d = bf_hi(y[j].y); s += (a * a + b * b) + (c * c + d * d); }
;         const float rs = rsqrtf(wave_sum(s) * (1.f / D) + EPS) * scale; float s2 = 0.f;
.LBB0_1324:
	s_nop 0
	s_waitcnt vmcnt(8)
	v_lshlrev_b32_e32 v68, 16, v66
	v_and_b32_e32 v69, 0xffff0000, v66
	v_lshlrev_b32_e32 v70, 16, v67
	v_and_b32_e32 v71, 0xffff0000, v67
	v_lshlrev_b32_e32 v66, 16, v64
	v_and_b32_e32 v67, 0xffff0000, v64
	v_lshlrev_b32_e32 v64, 16, v65
	v_and_b32_e32 v65, 0xffff0000, v65
	v_lshlrev_b32_e32 v80, 16, v62
	v_and_b32_e32 v81, 0xffff0000, v62
	v_lshlrev_b32_e32 v62, 16, v63
	v_and_b32_e32 v63, 0xffff0000, v63
	v_mov_b32_e32 v94, v69
	v_mov_b32_e32 v95, v67
	v_mov_b32_e32 v98, v71
	v_mov_b32_e32 v99, v65
	v_mov_b32_e32 v92, v68
	v_mov_b32_e32 v93, v66
	v_mov_b32_e32 v96, v70
	v_mov_b32_e32 v97, v64
	v_mov_b32_e32 v102, v81
	v_mov_b32_e32 v103, v63
	v_pk_mul_f32 v[94:95], v[94:95], v[94:95]
	v_pk_mul_f32 v[98:99], v[98:99], v[98:99]
	v_lshlrev_b32_e32 v82, 16, v60
	v_and_b32_e32 v83, 0xffff0000, v60
	v_lshlrev_b32_e32 v60, 16, v61
	v_and_b32_e32 v61, 0xffff0000, v61
	v_mov_b32_e32 v100, v80
	v_mov_b32_e32 v101, v62
	v_pk_mul_f32 v[102:103], v[102:103], v[102:103]
	v_pk_fma_f32 v[92:93], v[92:93], v[92:93], v[94:95]
	v_pk_fma_f32 v[94:95], v[96:97], v[96:97], v[98:99]
	v_lshlrev_b32_e32 v84, 16, v58
	v_and_b32_e32 v85, 0xffff0000, v58
	v_lshlrev_b32_e32 v58, 16, v59
	v_and_b32_e32 v59, 0xffff0000, v59
	v_mul_f32_e32 v104, v83, v83
	v_mul_f32_e32 v106, v61, v61
	v_pk_fma_f32 v[96:97], v[100:101], v[100:101], v[102:103]
	v_pk_add_f32 v[92:93], v[92:93], v[94:95]
	v_lshlrev_b32_e32 v86, 16, v56
	v_and_b32_e32 v87, 0xffff0000, v56
	v_lshlrev_b32_e32 v56, 16, v57
	v_and_b32_e32 v57, 0xffff0000, v57
	v_pk_mul_f32 v[108:109], v[84:85], v[84:85]
	v_pk_mul_f32 v[110:111], v[58:59], v[58:59]
	v_pk_fma_f32 v[104:105], v[82:83], v[82:83], v[104:105] op_sel_hi:[1,1,0]
	v_pk_fma_f32 v[106:107], v[60:61], v[60:61], v[106:107] op_sel_hi:[1,1,0]
	v_pk_add_f32 v[94:95], v[96:97], v[96:97] op_sel:[0,1] op_sel_hi:[1,0]
	v_pk_add_f32 v[92:93], v[92:93], v[92:93] op_sel:[0,1] op_sel_hi:[1,0]
	v_mov_b32_e32 v114, v87
	v_mov_b32_e32 v115, v57
	v_mov_b32_e32 v105, v110
	v_mov_b32_e32 v107, v111
	v_mov_b32_e32 v95, v109
	v_mov_b32_e32 v93, v108
	v_lshlrev_b32_e32 v88, 16, v54
	v_and_b32_e32 v89, 0xffff0000, v54
	v_lshlrev_b32_e32 v54, 16, v55
	v_and_b32_e32 v55, 0xffff0000, v55
	v_mov_b32_e32 v112, v86
	v_mov_b32_e32 v113, v56
	v_pk_mul_f32 v[114:115], v[114:115], v[114:115]
	v_pk_add_f32 v[96:97], v[104:105], v[106:107]
	v_pk_add_f32 v[92:93], v[92:93], v[94:95]
	v_lshlrev_b32_e32 v90, 16, v52
	v_and_b32_e32 v91, 0xffff0000, v52
	v_lshlrev_b32_e32 v52, 16, v53
	v_and_b32_e32 v53, 0xffff0000, v53
	v_mul_f32_e32 v116, v89, v89
	v_mul_f32_e32 v118, v55, v55
	v_pk_fma_f32 v[98:99], v[112:113], v[112:113], v[114:115]
	v_pk_add_f32 v[92:93], v[92:93], v[96:97]
	v_pk_mul_f32 v[120:121], v[90:91], v[90:91]
	v_pk_mul_f32 v[122:123], v[52:53], v[52:53]
	v_pk_fma_f32 v[116:117], v[88:89], v[88:89], v[116:117] op_sel_hi:[1,1,0]
	v_pk_fma_f32 v[118:119], v[54:55], v[54:55], v[118:119] op_sel_hi:[1,1,0]
	v_pk_add_f32 v[98:99], v[98:99], v[98:99] op_sel:[0,1] op_sel_hi:[1,0]
	v_pk_add_f32 v[92:93], v[92:93], v[92:93] op_sel:[0,1] op_sel_hi:[1,0]
	v_mov_b32_e32 v117, v122
	v_mov_b32_e32 v119, v123
	v_mov_b32_e32 v99, v121
	v_mov_b32_e32 v93, v120
	v_pk_add_f32 v[100:101], v[116:117], v[118:119]
	v_pk_add_f32 v[92:93], v[92:93], v[98:99]
	s_add_i32 s5, s74, s72
	v_pk_add_f32 v[92:93], v[92:93], v[100:101]
	s_cmp_lt_i32 s5, 0x8800
	v_add_f32_e32 v79, v92, v93
	ds_bpermute_b32 v92, v72, v79
	s_cselect_b64 s[0:1], -1, 0
	s_and_b64 vcc, s[0:1], exec
	s_cselect_b32 s0, s5, s74
	s_ashr_i32 s1, s0, 31
	s_waitcnt lgkmcnt(0)
	v_add_f32_e32 v79, v79, v92
	ds_bpermute_b32 v92, v73, v79
	s_lshl_b64 s[0:1], s[0:1], 12
	v_lshl_add_u64 v[102:103], v[4:5], 0, s[0:1]
	v_lshl_add_u64 v[104:105], v[6:7], 0, s[0:1]
	global_load_dwordx2 v[94:95], v[102:103], off nt
	global_load_dwordx2 v[106:107], v[102:103], off offset:512 nt
	global_load_dwordx2 v[108:109], v[102:103], off offset:1024 nt
	global_load_dwordx2 v[110:111], v[102:103], off offset:1536 nt
	global_load_dwordx2 v[112:113], v[102:103], off offset:2048 nt
	global_load_dwordx2 v[114:115], v[102:103], off offset:2560 nt
	global_load_dwordx2 v[116:117], v[102:103], off offset:3072 nt
	global_load_dwordx2 v[118:119], v[102:103], off offset:3584 nt
	global_load_dwordx2 v[122:123], v[104:105], off nt
	global_load_dwordx2 v[124:125], v[104:105], off offset:512 nt
	global_load_dwordx2 v[126:127], v[104:105], off offset:1024 nt
	global_load_dwordx2 v[128:129], v[104:105], off offset:1536 nt
	s_nop 0
	global_load_dwordx2 v[102:103], v[104:105], off offset:2048 nt
	global_load_dwordx2 v[130:131], v[104:105], off offset:2560 nt
	global_load_dwordx2 v[132:133], v[104:105], off offset:3072 nt
	s_nop 0
	global_load_dwordx2 v[104:105], v[104:105], off offset:3584 nt
	s_waitcnt lgkmcnt(0)
	v_add_f32_e32 v79, v79, v92
	ds_bpermute_b32 v92, v74, v79
	s_mov_b32 s74, s5
	s_waitcnt lgkmcnt(0)
; __device__ __forceinline__ unsigned cvt_pk_bf16(float lo, float hi) { const f32x2_cv v = {lo, hi}; return __builtin_bit_cast(unsigned, __builtin_convertvector(v, bf16x2_cv)); }
; __device__ __forceinline__ float bf_lo(unsigned u) { return __uint_as_float(u << 16); }
; __device__ __forceinline__ float bf_hi(unsigned u) { return __uint_as_float(u & 0xffff0000u); }
; template <bool XIN_BF, bool XOUT_BF>
; __device__ __forceinline__ void norm_pass(const float* xp, const float* xs, const bf16_t* xbin, const bf16_t* Y, const float* post, float scale, const float* pre, float* X, bf16_t* xbout, bf16_t* XN, int gw, int NGW, int lane, const float* PART = nullptr) {
;     ...
;         const float rs = rsqrtf(wave_sum(s) * (1.f / D) + EPS) * scale; float s2 = 0.f;
; #pragma unroll
;         for (int j = 0; j < 8; ++j) { const f32x4 g = ((const f32x4*)post + lane)[64 * j];
;             v[j].x += bf_lo(y[j].x) * rs * g.x; v[j].y += bf_hi(y[j].x) * rs * g.y; v[j].z += bf_lo(y[j].y) * rs * g.z; v[j].w += bf_hi(y[j].y) * rs * g.w;
;             s2 += (v[j].x * v[j].x + v[j].y * v[j].y) + (v[j].z * v[j].z + v[j].w * v[j].w);
;             if (XOUT_BF) { u32x2 w; w.x = cvt_pk_bf16(v[j].x, v[j].y); w.y = cvt_pk_bf16(v[j].z, v[j].w); __builtin_nontemporal_store(w, &((u32x2*)(xbout + (size_t)m * D) + lane)[64 * j]); }
;             else __builtin_nontemporal_store(v[j], &((f32x4*)(X + (size_t)m * D) + lane)[64 * j]); }
;     ...
;         for (int j = 0; j < 8; ++j) { v[j] = vn[j]; y[j] = yn[j]; }
	v_add_f32_e32 v79, v79, v92
	ds_bpermute_b32 v92, v75, v79
	s_waitcnt lgkmcnt(0)
	v_add_f32_e32 v79, v79, v92
	ds_bpermute_b32 v92, v76, v79
	s_waitcnt lgkmcnt(0)
	v_add_f32_e32 v79, v79, v92
	ds_bpermute_b32 v92, v77, v79
	s_waitcnt lgkmcnt(0)
	v_add_f32_e32 v79, v79, v92
	v_fmamk_f32 v79, v79, 0x3a000000, v78
	v_mul_f32_e32 v92, 0x4b800000, v79
	v_cmp_gt_f32_e64 s[0:1], s4, v79
	s_nop 1
	v_cndmask_b32_e64 v79, v79, v92, s[0:1]
	v_rsq_f32_e32 v79, v79
	s_nop 0
	v_mul_f32_e32 v92, 0x45800000, v79
	v_cndmask_b32_e64 v92, v79, v92, s[0:1]
	v_pk_mul_f32 v[68:69], v[92:93], v[68:69] op_sel_hi:[0,1]
	v_pk_mul_f32 v[70:71], v[92:93], v[70:71] op_sel_hi:[0,1]
	s_waitcnt vmcnt(23)
	v_pk_fma_f32 v[0:1], v[136:137], v[68:69], v[48:49]
	v_pk_fma_f32 v[2:3], v[138:139], v[70:71], v[50:51]
	global_store_dwordx4 v[22:23], v[0:3], off offset:-4096 nt
	s_nop 0
	v_pk_mul_f32 v[48:49], v[92:93], v[66:67] op_sel_hi:[0,1]
	v_pk_mul_f32 v[50:51], v[92:93], v[64:65] op_sel_hi:[0,1]
	v_pk_mul_f32 v[68:69], v[92:93], v[90:91] op_sel_hi:[0,1]
	v_pk_mul_f32 v[70:71], v[92:93], v[52:53] op_sel_hi:[0,1]
	s_waitcnt vmcnt(12)
	v_lshlrev_b32_e32 v79, 16, v112
	s_waitcnt vmcnt(10)
	v_and_b32_e32 v90, 0xffff0000, v117
	s_waitcnt vmcnt(9)
	v_lshlrev_b32_e32 v91, 16, v118
	s_waitcnt vmcnt(8)
	v_mov_b64_e32 v[66:67], v[122:123]
	s_waitcnt vmcnt(7)
	v_mov_b64_e32 v[64:65], v[124:125]
	s_waitcnt vmcnt(1)
	v_mov_b64_e32 v[52:53], v[104:105]
	v_pk_fma_f32 v[0:1], v[140:141], v[48:49], v[44:45]
	v_pk_fma_f32 v[2:3], v[142:143], v[50:51], v[46:47]
	global_store_dwordx4 v[22:23], v[0:3], off offset:-3072 nt
	s_nop 0
	v_pk_mul_f32 v[44:45], v[92:93], v[80:81] op_sel_hi:[0,1]
	v_pk_mul_f32 v[46:47], v[92:93], v[62:63] op_sel_hi:[0,1]
	v_lshlrev_b32_e32 v48, 16, v94
	v_and_b32_e32 v49, 0xffff0000, v94
	v_and_b32_e32 v80, 0xffff0000, v112
	v_lshlrev_b32_e32 v81, 16, v113
	v_and_b32_e32 v94, 0xffff0000, v119
	v_lshlrev_b32_e32 v50, 16, v95
	v_and_b32_e32 v51, 0xffff0000, v95
	v_mov_b64_e32 v[62:63], v[126:127]
	v_pk_fma_f32 v[0:1], v[144:145], v[44:45], v[40:41]
	v_pk_fma_f32 v[2:3], v[146:147], v[46:47], v[42:43]
	global_store_dwordx4 v[22:23], v[0:3], off offset:-2048 nt
	s_nop 0
	v_pk_mul_f32 v[40:41], v[92:93], v[82:83] op_sel_hi:[0,1]
	v_pk_mul_f32 v[42:43], v[92:93], v[60:61] op_sel_hi:[0,1]
	v_and_b32_e32 v82, 0xffff0000, v113
	v_lshlrev_b32_e32 v83, 16, v114
	v_lshlrev_b32_e32 v44, 16, v106
	v_and_b32_e32 v45, 0xffff0000, v106
	v_lshlrev_b32_e32 v46, 16, v107
	v_and_b32_e32 v47, 0xffff0000, v107
	v_mov_b64_e32 v[60:61], v[128:129]
	v_pk_fma_f32 v[0:1], v[148:149], v[40:41], v[36:37]
	v_pk_fma_f32 v[2:3], v[150:151], v[42:43], v[38:39]
	global_store_dwordx4 v[22:23], v[0:3], off offset:-1024 nt
	s_nop 0
	v_pk_mul_f32 v[36:37], v[92:93], v[84:85] op_sel_hi:[0,1]
	v_pk_mul_f32 v[38:39], v[92:93], v[58:59] op_sel_hi:[0,1]
	v_and_b32_e32 v84, 0xffff0000, v114
	v_lshlrev_b32_e32 v85, 16, v115
	v_lshlrev_b32_e32 v40, 16, v108
	v_and_b32_e32 v41, 0xffff0000, v108
	v_lshlrev_b32_e32 v42, 16, v109
	v_and_b32_e32 v43, 0xffff0000, v109
	v_mov_b64_e32 v[58:59], v[102:103]
	v_pk_fma_f32 v[0:1], v[152:153], v[36:37], v[32:33]
	v_pk_fma_f32 v[2:3], v[154:155], v[38:39], v[34:35]
	global_store_dwordx4 v[22:23], v[0:3], off nt
	s_nop 0
	v_pk_mul_f32 v[32:33], v[92:93], v[86:87] op_sel_hi:[0,1]
	v_pk_mul_f32 v[34:35], v[92:93], v[56:57] op_sel_hi:[0,1]
	v_and_b32_e32 v86, 0xffff0000, v115
	v_lshlrev_b32_e32 v87, 16, v116
	v_lshlrev_b32_e32 v36, 16, v110
	v_and_b32_e32 v37, 0xffff0000, v110
	v_lshlrev_b32_e32 v38, 16, v111
	v_and_b32_e32 v39, 0xffff0000, v111
	v_mov_b64_e32 v[56:57], v[130:131]
	v_pk_fma_f32 v[0:1], v[32:33], v[156:157], v[28:29]
	v_pk_fma_f32 v[2:3], v[34:35], v[158:159], v[30:31]
	global_store_dwordx4 v[22:23], v[0:3], off offset:1024 nt
	s_nop 0
	v_pk_mul_f32 v[28:29], v[92:93], v[88:89] op_sel_hi:[0,1]
	v_pk_mul_f32 v[30:31], v[92:93], v[54:55] op_sel_hi:[0,1]
	v_and_b32_e32 v88, 0xffff0000, v116
	v_lshlrev_b32_e32 v89, 16, v117
	v_and_b32_e32 v92, 0xffff0000, v118
	v_lshlrev_b32_e32 v93, 16, v119
	v_mov_b64_e32 v[54:55], v[132:133]
	v_mov_b32_e32 v32, v79
	v_mov_b32_e32 v33, v80
	v_mov_b32_e32 v34, v81
	v_mov_b32_e32 v35, v82
	v_pk_fma_f32 v[0:1], v[28:29], v[160:161], v[24:25]
	v_pk_fma_f32 v[2:3], v[30:31], v[162:163], v[26:27]
	global_store_dwordx4 v[22:23], v[0:3], off offset:2048 nt
	s_nop 0
	v_mov_b32_e32 v28, v83
	v_mov_b32_e32 v29, v84
	v_mov_b32_e32 v30, v85
	v_mov_b32_e32 v31, v86
	v_mov_b32_e32 v24, v87
	v_mov_b32_e32 v25, v88
	v_mov_b32_e32 v26, v89
	v_mov_b32_e32 v27, v90
	v_pk_fma_f32 v[0:1], v[68:69], v[164:165], v[8:9]
	v_pk_fma_f32 v[2:3], v[70:71], v[166:167], v[10:11]
	v_mov_b32_e32 v8, v91
	v_mov_b32_e32 v9, v92
	v_mov_b32_e32 v10, v93
	v_mov_b32_e32 v11, v94
	global_store_dwordx4 v[22:23], v[0:3], off offset:3072 nt
	v_lshl_add_u64 v[22:23], v[22:23], 0, s[2:3]
	s_cbranch_vccnz .LBB0_1324
